# RMSNorm streaming loops (phase 0/A, F, A): 72 serialized ds_bpermute butterfly steps replaced by DPP mov + permlane16/32_swap
# baseline (speedup 1.0000x reference)
; __device__ __forceinline__ unsigned cvt_pk_bf16(float lo, float hi) { f32x2 v = {lo, hi}; bf16x2_t b = __builtin_convertvector(v, bf16x2_t); return __builtin_bit_cast(unsigned, b); }
; __device__ __forceinline__ float shx(float v, int o, int lane) { return __int_as_float(__builtin_amdgcn_ds_bpermute((lane ^ o) << 2, __float_as_int(v))); }
; __device__ __forceinline__ float wave_sum(float v, int lane) {
; #pragma unroll
;     for (int o = 1; o < 64; o <<= 1) v += shx(v, o, lane);
;     return v;
; __device__ __forceinline__ void phase_a(const float* x, bf16_t* xb, float* rs, int gw, int ngw) {
;     ...
;     for (int m0 = gw * 4; m0 < GT; m0 += ngw * 4) {
;         f32x4 v[4][4];
; #pragma unroll
;         for (int q = 0; q < 4; ++q) { const f32x4* xr = (const f32x4*)(x + (size_t)(m0 + q) * DM) + lane;
; #pragma unroll
;             for (int j = 0; j < 4; ++j) v[q][j] = __builtin_nontemporal_load(xr + 64 * j); }
; #pragma unroll
;         for (int q = 0; q < 4; ++q) { float s = 0.f;
; #pragma unroll
;             for (int j = 0; j < 4; ++j) s += (v[q][j].x * v[q][j].x + v[q][j].y * v[q][j].y) + (v[q][j].z * v[q][j].z + v[q][j].w * v[q][j].w);
;             const float r = 1.0f / sqrtf(wave_sum(s, lane) * (1.0f / DM) + EPS);
;             if (lane == 0) rs[m0 + q] = r;
;             u32x2* o8 = (u32x2*)(xb + (size_t)(m0 + q) * DM) + lane;
; #pragma unroll
;             for (int j = 0; j < 4; ++j) { u32x2 w; w.x = cvt_pk_bf16(v[q][j].x, v[q][j].y); w.y = cvt_pk_bf16(v[q][j].z, v[q][j].w); o8[64 * j] = w; } }
.LBB0_53:
	v_add_co_u32_e32 v18, vcc, 0xffffd000, v70
	s_nop 1
	v_addc_co_u32_e32 v19, vcc, -1, v71, vcc
	global_load_dwordx4 v[62:65], v[18:19], off offset:-3072 nt
	global_load_dwordx4 v[58:61], v[18:19], off offset:-2048 nt
	global_load_dwordx4 v[54:57], v[18:19], off offset:-1024 nt
	global_load_dwordx4 v[50:53], v[18:19], off nt
	global_load_dwordx4 v[6:9], v[70:71], off offset:-3072 nt
	global_load_dwordx4 v[2:5], v[70:71], off offset:-2048 nt
	global_load_dwordx4 v[14:17], v[70:71], off offset:-1024 nt
	global_load_dwordx4 v[10:13], v[70:71], off nt
	v_add_co_u32_e32 v18, vcc, 0xffffe000, v70
	s_waitcnt vmcnt(6)
	v_mul_f32_e32 v80, v59, v59
	v_addc_co_u32_e32 v19, vcc, -1, v71, vcc
	v_add_co_u32_e32 v78, vcc, 0xfffff000, v70
	global_load_dwordx4 v[46:49], v[18:19], off offset:-3072 nt
	global_load_dwordx4 v[42:45], v[18:19], off offset:-2048 nt
	global_load_dwordx4 v[38:41], v[18:19], off offset:-1024 nt
	global_load_dwordx4 v[34:37], v[18:19], off nt
	v_addc_co_u32_e32 v79, vcc, -1, v71, vcc
	global_load_dwordx4 v[30:33], v[78:79], off offset:-3072 nt
	global_load_dwordx4 v[26:29], v[78:79], off offset:-2048 nt
	s_waitcnt lgkmcnt(0)
	global_load_dwordx4 v[22:25], v[78:79], off offset:-1024 nt
	global_load_dwordx4 v[18:21], v[70:71], off offset:-4096 nt
	v_mul_f32_e32 v78, v63, v63
	v_mul_f32_e32 v79, v65, v65
	v_mul_f32_e32 v81, v61, v61
	s_waitcnt vmcnt(13)
	v_mul_f32_e32 v82, v55, v55
	v_mul_f32_e32 v83, v57, v57
	v_fmac_f32_e32 v78, v62, v62
	v_fmac_f32_e32 v79, v64, v64
	v_fmac_f32_e32 v80, v58, v58
	v_fmac_f32_e32 v81, v60, v60
	s_waitcnt vmcnt(12)
	v_mul_f32_e32 v84, v51, v51
	v_mul_f32_e32 v85, v53, v53
	v_fmac_f32_e32 v82, v54, v54
	v_fmac_f32_e32 v83, v56, v56
	v_add_f32_e32 v78, v78, v79
	v_add_f32_e32 v79, v80, v81
	v_fmac_f32_e32 v84, v50, v50
	v_fmac_f32_e32 v85, v52, v52
	v_add_f32_e32 v80, v82, v83
	v_add_f32_e32 v78, v78, v79
	v_add_f32_e32 v81, v84, v85
	v_add_f32_e32 v78, v78, v80
	v_add_f32_e32 v78, v78, v81
	s_nop 1
	v_mov_b32_dpp v79, v78 quad_perm:[1,0,3,2] row_mask:0xf bank_mask:0xf
	s_waitcnt lgkmcnt(0)
	v_add_f32_e32 v78, v78, v79
	s_nop 1
	v_mov_b32_dpp v79, v78 quad_perm:[2,3,0,1] row_mask:0xf bank_mask:0xf
	s_waitcnt lgkmcnt(0)
	v_add_f32_e32 v78, v78, v79
	s_nop 1
	v_mov_b32_dpp v79, v78 row_half_mirror row_mask:0xf bank_mask:0xf
	s_waitcnt lgkmcnt(0)
	v_add_f32_e32 v78, v78, v79
	s_nop 1
	v_mov_b32_dpp v79, v78 row_ror:8 row_mask:0xf bank_mask:0xf
	s_waitcnt lgkmcnt(0)
	v_add_f32_e32 v78, v78, v79
	v_mov_b32_e32 v79, v78
	s_nop 1
	v_permlane16_swap_b32_e32 v79, v78
	s_waitcnt lgkmcnt(0)
	v_add_f32_e32 v78, v78, v79
	v_mov_b32_e32 v79, v78
	s_nop 1
	v_permlane32_swap_b32_e32 v79, v78
	s_and_saveexec_b64 s[28:29], s[4:5]
	s_cbranch_execz .LBB0_55
	s_waitcnt lgkmcnt(0)
	v_add_f32_e32 v78, v78, v79
	v_fmamk_f32 v78, v78, 0x3a800000, v66
	v_mul_f32_e32 v79, 0x4f800000, v78
	v_cmp_gt_f32_e32 vcc, s13, v78
	s_nop 1
	v_cndmask_b32_e32 v78, v78, v79, vcc
	v_sqrt_f32_e32 v79, v78
	s_nop 0
	v_add_u32_e32 v80, -1, v79
	v_fma_f32 v82, -v80, v79, v78
	v_add_u32_e32 v81, 1, v79
	v_cmp_ge_f32_e64 s[6:7], 0, v82
	s_nop 1
	v_cndmask_b32_e64 v80, v79, v80, s[6:7]
	v_fma_f32 v79, -v81, v79, v78
	v_cmp_lt_f32_e64 s[6:7], 0, v79
	s_nop 1
	v_cndmask_b32_e64 v79, v80, v81, s[6:7]
	v_mul_f32_e32 v80, 0x37800000, v79
	v_cndmask_b32_e32 v79, v79, v80, vcc
	v_cmp_class_f32_e32 vcc, v78, v77
	s_nop 1
	v_cndmask_b32_e32 v78, v79, v78, vcc
	v_div_scale_f32 v79, s[6:7], v78, v78, 1.0
	v_rcp_f32_e32 v80, v79
	s_nop 0
	v_fma_f32 v81, -v79, v80, 1.0
	v_fmac_f32_e32 v80, v81, v80
	v_div_scale_f32 v81, vcc, 1.0, v78, 1.0
	v_mul_f32_e32 v82, v81, v80
	v_fma_f32 v83, -v79, v82, v81
	v_fmac_f32_e32 v82, v83, v80
	v_fma_f32 v79, -v79, v82, v81
	v_div_fmas_f32 v79, v79, v80, v82
	v_div_fixup_f32 v78, v79, v78, 1.0
	global_store_dword v67, v78, s[20:21] offset:-12
.LBB0_55:
	s_or_b64 exec, exec, s[28:29]
	s_waitcnt vmcnt(7)
	v_mul_f32_e32 v78, v47, v47
	s_waitcnt lgkmcnt(0)
	v_mul_f32_e32 v79, v49, v49
	v_fmac_f32_e32 v78, v46, v46
	v_fmac_f32_e32 v79, v48, v48
	v_add_f32_e32 v78, v78, v79
	s_waitcnt vmcnt(6)
	v_mul_f32_e32 v79, v43, v43
	v_mul_f32_e32 v80, v45, v45
	v_fmac_f32_e32 v79, v42, v42
	v_fmac_f32_e32 v80, v44, v44
	v_add_f32_e32 v79, v79, v80
	v_add_f32_e32 v78, v78, v79
	s_waitcnt vmcnt(5)
	v_mul_f32_e32 v79, v39, v39
	v_mul_f32_e32 v80, v41, v41
	v_fmac_f32_e32 v79, v38, v38
	v_fmac_f32_e32 v80, v40, v40
	v_add_f32_e32 v79, v79, v80
	v_add_f32_e32 v78, v78, v79
	s_waitcnt vmcnt(4)
	v_mul_f32_e32 v79, v35, v35
	v_mul_f32_e32 v80, v37, v37
	v_fmac_f32_e32 v79, v34, v34
	v_fmac_f32_e32 v80, v36, v36
	v_add_f32_e32 v79, v79, v80
	v_add_f32_e32 v78, v78, v79
	s_nop 1
	v_mov_b32_dpp v79, v78 quad_perm:[1,0,3,2] row_mask:0xf bank_mask:0xf
	v_cvt_pk_bf16_f32 v62, v62, v63
	v_cvt_pk_bf16_f32 v63, v64, v65
	v_add_co_u32_e32 v64, vcc, 0xfffff000, v68
	s_waitcnt lgkmcnt(0)
	v_add_f32_e32 v78, v78, v79
	s_nop 1
	v_mov_b32_dpp v79, v78 quad_perm:[2,3,0,1] row_mask:0xf bank_mask:0xf
	v_addc_co_u32_e32 v65, vcc, -1, v69, vcc
	global_store_dwordx2 v[64:65], v[62:63], off offset:-3584
	v_cvt_pk_bf16_f32 v58, v58, v59
	s_waitcnt lgkmcnt(0)
	v_add_f32_e32 v78, v78, v79
	s_nop 1
	v_mov_b32_dpp v79, v78 row_half_mirror row_mask:0xf bank_mask:0xf
	v_cvt_pk_bf16_f32 v59, v60, v61
	global_store_dwordx2 v[64:65], v[58:59], off offset:-3072
	v_cvt_pk_bf16_f32 v58, v54, v55
	v_cvt_pk_bf16_f32 v59, v56, v57
	s_waitcnt lgkmcnt(0)
	v_add_f32_e32 v78, v78, v79
	s_nop 1
	v_mov_b32_dpp v79, v78 row_ror:8 row_mask:0xf bank_mask:0xf
	v_cvt_pk_bf16_f32 v50, v50, v51
	v_cvt_pk_bf16_f32 v51, v52, v53
	global_store_dwordx2 v[64:65], v[58:59], off offset:-2560
	global_store_dwordx2 v[64:65], v[50:51], off offset:-2048
	s_waitcnt lgkmcnt(0)
	v_add_f32_e32 v62, v78, v79
	v_mov_b32_e32 v63, v62
	s_nop 1
	v_permlane16_swap_b32_e32 v63, v62
	s_waitcnt lgkmcnt(0)
	v_add_f32_e32 v54, v62, v63
	v_mov_b32_e32 v55, v54
	s_nop 1
	v_permlane32_swap_b32_e32 v55, v54
	s_and_saveexec_b64 s[28:29], s[4:5]
	s_cbranch_execz .LBB0_57
; __device__ __forceinline__ unsigned cvt_pk_bf16(float lo, float hi) { f32x2 v = {lo, hi}; bf16x2_t b = __builtin_convertvector(v, bf16x2_t); return __builtin_bit_cast(unsigned, b); }
; __device__ __forceinline__ float shx(float v, int o, int lane) { return __int_as_float(__builtin_amdgcn_ds_bpermute((lane ^ o) << 2, __float_as_int(v))); }
; __device__ __forceinline__ float wave_sum(float v, int lane) {
; #pragma unroll
;     for (int o = 1; o < 64; o <<= 1) v += shx(v, o, lane);
;     return v;
; __device__ __forceinline__ void phase_a(const float* x, bf16_t* xb, float* rs, int gw, int ngw) {
;     ...
;         for (int q = 0; q < 4; ++q) { float s = 0.f;
; #pragma unroll
;             for (int j = 0; j < 4; ++j) s += (v[q][j].x * v[q][j].x + v[q][j].y * v[q][j].y) + (v[q][j].z * v[q][j].z + v[q][j].w * v[q][j].w);
;             const float r = 1.0f / sqrtf(wave_sum(s, lane) * (1.0f / DM) + EPS);
;             if (lane == 0) rs[m0 + q] = r;
;             u32x2* o8 = (u32x2*)(xb + (size_t)(m0 + q) * DM) + lane;
; #pragma unroll
;             for (int j = 0; j < 4; ++j) { u32x2 w; w.x = cvt_pk_bf16(v[q][j].x, v[q][j].y); w.y = cvt_pk_bf16(v[q][j].z, v[q][j].w); o8[64 * j] = w; } }
	s_waitcnt lgkmcnt(0)
	v_add_f32_e32 v50, v54, v55
	v_fmamk_f32 v50, v50, 0x3a800000, v66
	v_mul_f32_e32 v51, 0x4f800000, v50
	v_cmp_gt_f32_e32 vcc, s13, v50
	s_nop 1
	v_cndmask_b32_e32 v50, v50, v51, vcc
	v_sqrt_f32_e32 v51, v50
	s_nop 0
	v_add_u32_e32 v52, -1, v51
	v_fma_f32 v54, -v52, v51, v50
	v_add_u32_e32 v53, 1, v51
	v_cmp_ge_f32_e64 s[6:7], 0, v54
	s_nop 1
	v_cndmask_b32_e64 v52, v51, v52, s[6:7]
	v_fma_f32 v51, -v53, v51, v50
	v_cmp_lt_f32_e64 s[6:7], 0, v51
	s_nop 1
	v_cndmask_b32_e64 v51, v52, v53, s[6:7]
	v_mul_f32_e32 v52, 0x37800000, v51
	v_cndmask_b32_e32 v51, v51, v52, vcc
	v_cmp_class_f32_e32 vcc, v50, v77
	s_nop 1
	v_cndmask_b32_e32 v50, v51, v50, vcc
	v_div_scale_f32 v51, s[6:7], v50, v50, 1.0
	v_rcp_f32_e32 v52, v51
	s_nop 0
	v_fma_f32 v53, -v51, v52, 1.0
	v_fmac_f32_e32 v52, v53, v52
	v_div_scale_f32 v53, vcc, 1.0, v50, 1.0
	v_mul_f32_e32 v54, v53, v52
	v_fma_f32 v55, -v51, v54, v53
	v_fmac_f32_e32 v54, v55, v52
	v_fma_f32 v51, -v51, v54, v53
	v_div_fmas_f32 v51, v51, v52, v54
	v_div_fixup_f32 v50, v51, v50, 1.0
	global_store_dword v67, v50, s[20:21] offset:-8
.LBB0_57:
	s_or_b64 exec, exec, s[28:29]
	s_waitcnt vmcnt(7)
	v_mul_f32_e32 v50, v31, v31
	v_mul_f32_e32 v51, v33, v33
	v_fmac_f32_e32 v50, v30, v30
	v_fmac_f32_e32 v51, v32, v32
	v_add_f32_e32 v50, v50, v51
	s_waitcnt vmcnt(6)
	v_mul_f32_e32 v51, v27, v27
	v_mul_f32_e32 v52, v29, v29
	v_fmac_f32_e32 v51, v26, v26
	v_fmac_f32_e32 v52, v28, v28
	v_add_f32_e32 v51, v51, v52
	v_add_f32_e32 v50, v50, v51
	s_waitcnt vmcnt(5)
	v_mul_f32_e32 v51, v23, v23
	v_mul_f32_e32 v52, v25, v25
	v_fmac_f32_e32 v51, v22, v22
	v_fmac_f32_e32 v52, v24, v24
	v_add_f32_e32 v51, v51, v52
	v_add_f32_e32 v50, v50, v51
	s_waitcnt vmcnt(4)
	v_mul_f32_e32 v51, v19, v19
	v_mul_f32_e32 v52, v21, v21
	v_fmac_f32_e32 v51, v18, v18
	v_fmac_f32_e32 v52, v20, v20
	v_add_f32_e32 v51, v51, v52
	v_add_f32_e32 v50, v50, v51
	s_nop 1
	v_mov_b32_dpp v51, v50 quad_perm:[1,0,3,2] row_mask:0xf bank_mask:0xf
	v_cvt_pk_bf16_f32 v46, v46, v47
	v_cvt_pk_bf16_f32 v47, v48, v49
	v_add_co_u32_e32 v48, vcc, 0xfffff000, v68
	s_waitcnt lgkmcnt(0)
	v_add_f32_e32 v50, v50, v51
	s_nop 1
	v_mov_b32_dpp v51, v50 quad_perm:[2,3,0,1] row_mask:0xf bank_mask:0xf
	v_addc_co_u32_e32 v49, vcc, -1, v69, vcc
	global_store_dwordx2 v[48:49], v[46:47], off offset:-1536
	v_cvt_pk_bf16_f32 v42, v42, v43
	s_waitcnt lgkmcnt(0)
	v_add_f32_e32 v50, v50, v51
	s_nop 1
	v_mov_b32_dpp v51, v50 row_half_mirror row_mask:0xf bank_mask:0xf
	v_cvt_pk_bf16_f32 v43, v44, v45
	global_store_dwordx2 v[48:49], v[42:43], off offset:-1024
	v_cvt_pk_bf16_f32 v42, v38, v39
	v_cvt_pk_bf16_f32 v43, v40, v41
	s_waitcnt lgkmcnt(0)
	v_add_f32_e32 v50, v50, v51
	s_nop 1
	v_mov_b32_dpp v51, v50 row_ror:8 row_mask:0xf bank_mask:0xf
	v_cvt_pk_bf16_f32 v34, v34, v35
	v_cvt_pk_bf16_f32 v35, v36, v37
	global_store_dwordx2 v[48:49], v[42:43], off offset:-512
	global_store_dwordx2 v[68:69], v[34:35], off offset:-4096
	s_waitcnt lgkmcnt(0)
	v_add_f32_e32 v46, v50, v51
	v_mov_b32_e32 v47, v46
	s_nop 1
	v_permlane16_swap_b32_e32 v47, v46
	s_waitcnt lgkmcnt(0)
	v_add_f32_e32 v38, v46, v47
	v_mov_b32_e32 v39, v38
	s_nop 1
	v_permlane32_swap_b32_e32 v39, v38
	s_and_saveexec_b64 s[28:29], s[4:5]
	s_cbranch_execz .LBB0_59
	s_waitcnt lgkmcnt(0)
	v_add_f32_e32 v34, v38, v39
	v_fmamk_f32 v34, v34, 0x3a800000, v66
	v_mul_f32_e32 v35, 0x4f800000, v34
	v_cmp_gt_f32_e32 vcc, s13, v34
	s_nop 1
	v_cndmask_b32_e32 v34, v34, v35, vcc
	v_sqrt_f32_e32 v35, v34
	s_nop 0
	v_add_u32_e32 v36, -1, v35
	v_fma_f32 v38, -v36, v35, v34
	v_add_u32_e32 v37, 1, v35
	v_cmp_ge_f32_e64 s[6:7], 0, v38
	s_nop 1
	v_cndmask_b32_e64 v36, v35, v36, s[6:7]
	v_fma_f32 v35, -v37, v35, v34
	v_cmp_lt_f32_e64 s[6:7], 0, v35
	s_nop 1
	v_cndmask_b32_e64 v35, v36, v37, s[6:7]
	v_mul_f32_e32 v36, 0x37800000, v35
	v_cndmask_b32_e32 v35, v35, v36, vcc
	v_cmp_class_f32_e32 vcc, v34, v77
	s_nop 1
	v_cndmask_b32_e32 v34, v35, v34, vcc
	v_div_scale_f32 v35, s[6:7], v34, v34, 1.0
	v_rcp_f32_e32 v36, v35
	s_nop 0
	v_fma_f32 v37, -v35, v36, 1.0
	v_fmac_f32_e32 v36, v37, v36
	v_div_scale_f32 v37, vcc, 1.0, v34, 1.0
	v_mul_f32_e32 v38, v37, v36
	v_fma_f32 v39, -v35, v38, v37
	v_fmac_f32_e32 v38, v39, v36
	v_fma_f32 v35, -v35, v38, v37
	v_div_fmas_f32 v35, v35, v36, v38
	v_div_fixup_f32 v34, v35, v34, 1.0
	global_store_dword v67, v34, s[20:21] offset:-4
; __device__ __forceinline__ unsigned cvt_pk_bf16(float lo, float hi) { f32x2 v = {lo, hi}; bf16x2_t b = __builtin_convertvector(v, bf16x2_t); return __builtin_bit_cast(unsigned, b); }
; __device__ __forceinline__ float shx(float v, int o, int lane) { return __int_as_float(__builtin_amdgcn_ds_bpermute((lane ^ o) << 2, __float_as_int(v))); }
; __device__ __forceinline__ float wave_sum(float v, int lane) {
; #pragma unroll
;     for (int o = 1; o < 64; o <<= 1) v += shx(v, o, lane);
;     return v;
; __device__ __forceinline__ void phase_a(const float* x, bf16_t* xb, float* rs, int gw, int ngw) {
;     ...
;         for (int q = 0; q < 4; ++q) { float s = 0.f;
; #pragma unroll
;             for (int j = 0; j < 4; ++j) s += (v[q][j].x * v[q][j].x + v[q][j].y * v[q][j].y) + (v[q][j].z * v[q][j].z + v[q][j].w * v[q][j].w);
;             const float r = 1.0f / sqrtf(wave_sum(s, lane) * (1.0f / DM) + EPS);
;             if (lane == 0) rs[m0 + q] = r;
;             u32x2* o8 = (u32x2*)(xb + (size_t)(m0 + q) * DM) + lane;
; #pragma unroll
;             for (int j = 0; j < 4; ++j) { u32x2 w; w.x = cvt_pk_bf16(v[q][j].x, v[q][j].y); w.y = cvt_pk_bf16(v[q][j].z, v[q][j].w); o8[64 * j] = w; } }
.LBB0_59:
	s_or_b64 exec, exec, s[28:29]
	v_mul_f32_e32 v34, v7, v7
	v_mul_f32_e32 v35, v9, v9
	v_fmac_f32_e32 v34, v6, v6
	v_fmac_f32_e32 v35, v8, v8
	v_add_f32_e32 v34, v34, v35
	v_mul_f32_e32 v35, v3, v3
	v_mul_f32_e32 v36, v5, v5
	v_fmac_f32_e32 v35, v2, v2
	v_fmac_f32_e32 v36, v4, v4
	v_add_f32_e32 v35, v35, v36
	v_add_f32_e32 v34, v34, v35
	v_mul_f32_e32 v35, v15, v15
	v_mul_f32_e32 v36, v17, v17
	v_fmac_f32_e32 v35, v14, v14
	v_fmac_f32_e32 v36, v16, v16
	v_add_f32_e32 v35, v35, v36
	v_add_f32_e32 v34, v34, v35
	v_mul_f32_e32 v35, v11, v11
	v_mul_f32_e32 v36, v13, v13
	v_fmac_f32_e32 v35, v10, v10
	v_fmac_f32_e32 v36, v12, v12
	v_add_f32_e32 v35, v35, v36
	v_add_f32_e32 v34, v34, v35
	s_nop 1
	v_mov_b32_dpp v35, v34 quad_perm:[1,0,3,2] row_mask:0xf bank_mask:0xf
	v_cvt_pk_bf16_f32 v30, v30, v31
	v_cvt_pk_bf16_f32 v31, v32, v33
	global_store_dwordx2 v[68:69], v[30:31], off offset:-3584
	v_cvt_pk_bf16_f32 v26, v26, v27
	s_waitcnt lgkmcnt(0)
	v_add_f32_e32 v34, v34, v35
	s_nop 1
	v_mov_b32_dpp v35, v34 quad_perm:[2,3,0,1] row_mask:0xf bank_mask:0xf
	v_cvt_pk_bf16_f32 v27, v28, v29
	global_store_dwordx2 v[68:69], v[26:27], off offset:-3072
	v_cvt_pk_bf16_f32 v26, v22, v23
	v_cvt_pk_bf16_f32 v27, v24, v25
	s_waitcnt lgkmcnt(0)
	v_add_f32_e32 v34, v34, v35
	s_nop 1
	v_mov_b32_dpp v35, v34 row_half_mirror row_mask:0xf bank_mask:0xf
	v_cvt_pk_bf16_f32 v18, v18, v19
	v_cvt_pk_bf16_f32 v19, v20, v21
	global_store_dwordx2 v[68:69], v[26:27], off offset:-2560
	global_store_dwordx2 v[68:69], v[18:19], off offset:-2048
	s_waitcnt lgkmcnt(0)
	v_add_f32_e32 v34, v34, v35
	s_nop 1
	v_mov_b32_dpp v35, v34 row_ror:8 row_mask:0xf bank_mask:0xf
	s_waitcnt lgkmcnt(0)
	v_add_f32_e32 v30, v34, v35
	v_mov_b32_e32 v31, v30
	s_nop 1
	v_permlane16_swap_b32_e32 v31, v30
	s_waitcnt lgkmcnt(0)
	v_add_f32_e32 v22, v30, v31
	v_mov_b32_e32 v23, v22
	s_nop 1
	v_permlane32_swap_b32_e32 v23, v22
	s_and_saveexec_b64 s[28:29], s[4:5]
	s_cbranch_execz .LBB0_52
	s_waitcnt lgkmcnt(0)
	v_add_f32_e32 v18, v22, v23
	v_fmamk_f32 v18, v18, 0x3a800000, v66
	v_mul_f32_e32 v19, 0x4f800000, v18
	v_cmp_gt_f32_e32 vcc, s13, v18
	s_nop 1
	v_cndmask_b32_e32 v18, v18, v19, vcc
	v_sqrt_f32_e32 v19, v18
	s_nop 0
	v_add_u32_e32 v20, -1, v19
	v_fma_f32 v22, -v20, v19, v18
	v_add_u32_e32 v21, 1, v19
	v_cmp_ge_f32_e64 s[6:7], 0, v22
	s_nop 1
	v_cndmask_b32_e64 v20, v19, v20, s[6:7]
	v_fma_f32 v19, -v21, v19, v18
	v_cmp_lt_f32_e64 s[6:7], 0, v19
	s_nop 1
	v_cndmask_b32_e64 v19, v20, v21, s[6:7]
	v_mul_f32_e32 v20, 0x37800000, v19
	v_cndmask_b32_e32 v19, v19, v20, vcc
	v_cmp_class_f32_e32 vcc, v18, v77
	s_nop 1
	v_cndmask_b32_e32 v18, v19, v18, vcc
	v_div_scale_f32 v19, s[6:7], v18, v18, 1.0
	v_rcp_f32_e32 v20, v19
	s_nop 0
	v_fma_f32 v21, -v19, v20, 1.0
	v_fmac_f32_e32 v20, v21, v20
	v_div_scale_f32 v21, vcc, 1.0, v18, 1.0
	v_mul_f32_e32 v22, v21, v20
	v_fma_f32 v23, -v19, v22, v21
	v_fmac_f32_e32 v22, v23, v20
	v_fma_f32 v19, -v19, v22, v21
	v_div_fmas_f32 v19, v19, v20, v22
	v_div_fixup_f32 v18, v19, v18, 1.0
	global_store_dword v67, v18, s[20:21]
	s_branch .LBB0_52

; __device__ __forceinline__ float bf_lo(unsigned w) { return __uint_as_float(w << 16); }
; __device__ __forceinline__ float bf_hi(unsigned w) { return __uint_as_float(w & 0xffff0000u); }
; __device__ __forceinline__ float shx(float v, int o, int lane) { return __int_as_float(__builtin_amdgcn_ds_bpermute((lane ^ o) << 2, __float_as_int(v))); }
; __device__ __forceinline__ float wave_sum(float v, int lane) {
; #pragma unroll
;     for (int o = 1; o < 64; o <<= 1) v += shx(v, o, lane);
;     return v;
; __device__ __forceinline__ void phase_f(const float* x, float* out, const bf16_t* ob, int ldo, const float* g_post, int gw, int ngw) {
;     ...
;     for (int m0 = gw * 4; m0 < GT; m0 += ngw * 4) {
;         u32x2 v[4][4]; f32x4 xv[4][4];
; #pragma unroll
;         for (int q = 0; q < 4; ++q) { const u32x2* orow = (const u32x2*)(ob + (size_t)(m0 + q) * ldo) + lane; const f32x4* xr = (const f32x4*)(x + (size_t)(m0 + q) * DM) + lane;
; #pragma unroll
;             for (int j = 0; j < 4; ++j) { v[q][j] = orow[64 * j]; xv[q][j] = __builtin_nontemporal_load(xr + 64 * j); } }
; #pragma unroll
;         for (int q = 0; q < 4; ++q) { float s = 0.f; f32x4 f[4];
; #pragma unroll
;             for (int j = 0; j < 4; ++j) { f[j] = (f32x4){bf_lo(v[q][j].x), bf_hi(v[q][j].x), bf_lo(v[q][j].y), bf_hi(v[q][j].y)}; s += (f[j].x * f[j].x + f[j].y * f[j].y) + (f[j].z * f[j].z + f[j].w * f[j].w); }
;             const float r = 1.0f / sqrtf(wave_sum(s, lane) * (1.0f / DM) + EPS);
.LBB0_444:
	s_nop 0
	v_add_co_u32_e32 v20, vcc, 0xffff3000, v82
	v_lshl_add_u64 v[18:19], s[12:13], 0, v[0:1]
	s_nop 0
	v_addc_co_u32_e32 v21, vcc, -1, v83, vcc
	global_load_dwordx2 v[108:109], v[20:21], off offset:-3584
	global_load_dwordx4 v[78:81], v[18:19], off nt
	global_load_dwordx2 v[110:111], v[20:21], off offset:-3072
	global_load_dwordx4 v[74:77], v[18:19], off offset:1024 nt
	global_load_dwordx2 v[112:113], v[20:21], off offset:-2560
	global_load_dwordx4 v[70:73], v[18:19], off offset:2048 nt
	global_load_dwordx2 v[132:133], v[20:21], off offset:-2048
	global_load_dwordx4 v[66:69], v[18:19], off offset:3072 nt
	v_add_co_u32_e32 v20, vcc, 0xffff7000, v82
	s_movk_i32 s6, 0xc000
	s_nop 0
	v_addc_co_u32_e32 v21, vcc, -1, v83, vcc
	v_add_co_u32_e32 v22, vcc, s31, v18
	global_load_dwordx2 v[104:105], v[20:21], off offset:-1536
	s_nop 0
	v_addc_co_u32_e32 v23, vcc, 0, v19, vcc
	v_add_co_u32_e32 v24, vcc, s87, v18
	s_add_i32 s11, s11, s22
	s_nop 0
	v_addc_co_u32_e32 v25, vcc, 0, v19, vcc
	global_load_dwordx4 v[62:65], v[24:25], off offset:-4096 nt
	global_load_dwordx2 v[106:107], v[20:21], off offset:-1024
	global_load_dwordx4 v[58:61], v[22:23], off offset:1024 nt
	global_load_dwordx2 v[102:103], v[20:21], off offset:-512
	global_load_dwordx4 v[54:57], v[22:23], off offset:2048 nt
	global_load_dwordx2 v[100:101], v[20:21], off
	global_load_dwordx4 v[50:53], v[22:23], off offset:3072 nt
	v_add_co_u32_e32 v20, vcc, s6, v82
	s_movk_i32 s6, 0x3000
	s_nop 0
	v_addc_co_u32_e32 v21, vcc, -1, v83, vcc
	v_add_co_u32_e32 v30, vcc, s6, v18
	global_load_dwordx2 v[98:99], v[20:21], off offset:-3584
	global_load_dwordx4 v[46:49], v[24:25], off nt
	global_load_dwordx2 v[96:97], v[20:21], off offset:-3072
	global_load_dwordx4 v[42:45], v[24:25], off offset:1024 nt
	global_load_dwordx2 v[94:95], v[20:21], off offset:-2560
	global_load_dwordx4 v[38:41], v[24:25], off offset:2048 nt
	global_load_dwordx2 v[92:93], v[20:21], off offset:-2048
	global_load_dwordx4 v[34:37], v[24:25], off offset:3072 nt
	global_load_dwordx2 v[84:85], v[82:83], off offset:-1536
	v_addc_co_u32_e32 v31, vcc, 0, v19, vcc
	global_load_dwordx4 v[18:21], v[30:31], off nt
	global_load_dwordx2 v[86:87], v[82:83], off offset:-1024
	global_load_dwordx4 v[22:25], v[30:31], off offset:1024 nt
	global_load_dwordx2 v[88:89], v[82:83], off offset:-512
	global_load_dwordx4 v[26:29], v[30:31], off offset:2048 nt
	global_load_dwordx2 v[90:91], v[82:83], off
	s_nop 0
	global_load_dwordx4 v[30:33], v[30:31], off offset:3072 nt
	s_add_u32 s12, s12, s52
	s_addc_u32 s13, s13, s53
	v_lshl_add_u64 v[82:83], v[82:83], 0, s[28:29]
	s_waitcnt vmcnt(31)
	v_and_b32_e32 v125, 0xffff0000, v109
	v_lshlrev_b32_e32 v122, 16, v108
	v_and_b32_e32 v123, 0xffff0000, v108
	v_lshlrev_b32_e32 v124, 16, v109
	v_mul_f32_e32 v108, v125, v125
	s_waitcnt vmcnt(29)
	v_and_b32_e32 v117, 0xffff0000, v111
	v_and_b32_e32 v116, 0xffff0000, v110
	v_pk_fma_f32 v[134:135], v[124:125], v[124:125], v[108:109] op_sel_hi:[1,1,0]
	v_lshlrev_b32_e32 v115, 16, v111
	v_lshlrev_b32_e32 v114, 16, v110
	v_pk_mul_f32 v[108:109], v[116:117], v[116:117]
	s_waitcnt vmcnt(25)
	v_and_b32_e32 v111, 0xffff0000, v132
	v_mul_f32_e32 v110, v123, v123
	v_pk_fma_f32 v[136:137], v[114:115], v[114:115], v[108:109]
	v_lshlrev_b32_e32 v120, 16, v113
	v_and_b32_e32 v121, 0xffff0000, v113
	v_lshlrev_b32_e32 v113, 16, v132
	v_lshlrev_b32_e32 v108, 16, v133
	v_and_b32_e32 v109, 0xffff0000, v133
	v_pk_fma_f32 v[132:133], v[122:123], v[122:123], v[110:111] op_sel_hi:[1,1,0]
	v_lshlrev_b32_e32 v118, 16, v112
	v_and_b32_e32 v119, 0xffff0000, v112
	v_mov_b32_e32 v112, v132
	v_mov_b32_e32 v138, v134
	v_mov_b32_e32 v139, v113
	v_pk_add_f32 v[132:133], v[132:133], v[134:135]
	v_pk_mul_f32 v[134:135], v[112:113], v[138:139]
	v_mul_f32_e32 v140, v111, v111
	v_mov_b32_e32 v133, v135
	v_pk_add_f32 v[134:135], v[136:137], v[136:137] op_sel:[0,1] op_sel_hi:[1,0]
	v_mul_f32_e32 v110, v119, v119
	v_mov_b32_e32 v135, v140
	v_pk_add_f32 v[132:133], v[132:133], v[134:135]
	v_pk_fma_f32 v[134:135], v[118:119], v[118:119], v[110:111] op_sel_hi:[1,1,0]
	v_mul_f32_e32 v110, v121, v121
	v_mul_f32_e32 v141, v108, v108
	v_mul_f32_e32 v142, v109, v109
	v_pk_fma_f32 v[136:137], v[120:121], v[120:121], v[110:111] op_sel_hi:[1,1,0]
	v_mov_b32_e32 v135, v141
	v_mov_b32_e32 v137, v142
	v_pk_add_f32 v[134:135], v[134:135], v[136:137]
	s_nop 0
	v_pk_add_f32 v[132:133], v[132:133], v[134:135]
	s_nop 0
	v_add_f32_e32 v110, v132, v133
	s_nop 1
	v_mov_b32_dpp v112, v110 quad_perm:[1,0,3,2] row_mask:0xf bank_mask:0xf
	s_waitcnt lgkmcnt(0)
	v_add_f32_e32 v110, v110, v112
	s_nop 1
	v_mov_b32_dpp v112, v110 quad_perm:[2,3,0,1] row_mask:0xf bank_mask:0xf
	s_waitcnt lgkmcnt(0)
	v_add_f32_e32 v110, v110, v112
	s_nop 1
	v_mov_b32_dpp v112, v110 row_half_mirror row_mask:0xf bank_mask:0xf
	s_waitcnt lgkmcnt(0)
	v_add_f32_e32 v110, v110, v112
	s_nop 1
	v_mov_b32_dpp v112, v110 row_ror:8 row_mask:0xf bank_mask:0xf
	s_waitcnt lgkmcnt(0)
	v_add_f32_e32 v110, v110, v112
	v_mov_b32_e32 v112, v110
	s_nop 1
	v_permlane16_swap_b32_e32 v112, v110
	s_waitcnt lgkmcnt(0)
	v_add_f32_e32 v110, v110, v112
	v_mov_b32_e32 v112, v110
	s_nop 1
	v_permlane32_swap_b32_e32 v112, v110
	s_waitcnt lgkmcnt(0)
; __device__ __forceinline__ float bf_lo(unsigned w) { return __uint_as_float(w << 16); }
; __device__ __forceinline__ float bf_hi(unsigned w) { return __uint_as_float(w & 0xffff0000u); }
; __device__ __forceinline__ float shx(float v, int o, int lane) { return __int_as_float(__builtin_amdgcn_ds_bpermute((lane ^ o) << 2, __float_as_int(v))); }
; __device__ __forceinline__ float wave_sum(float v, int lane) {
; #pragma unroll
;     for (int o = 1; o < 64; o <<= 1) v += shx(v, o, lane);
;     return v;
; __device__ __forceinline__ void phase_f(const float* x, float* out, const bf16_t* ob, int ldo, const float* g_post, int gw, int ngw) {
;     ...
;         for (int q = 0; q < 4; ++q) { float s = 0.f; f32x4 f[4];
; #pragma unroll
;             for (int j = 0; j < 4; ++j) { f[j] = (f32x4){bf_lo(v[q][j].x), bf_hi(v[q][j].x), bf_lo(v[q][j].y), bf_hi(v[q][j].y)}; s += (f[j].x * f[j].x + f[j].y * f[j].y) + (f[j].z * f[j].z + f[j].w * f[j].w); }
;             const float r = 1.0f / sqrtf(wave_sum(s, lane) * (1.0f / DM) + EPS);
;             f32x4* orow = (f32x4*)(out + (size_t)(m0 + q) * DM) + lane;
; #pragma unroll
;             for (int j = 0; j < 4; ++j) __builtin_nontemporal_store(xv[q][j] + f[j] * r * gp[j], orow + 64 * j); }
	v_add_f32_e32 v110, v110, v112
	v_fmamk_f32 v110, v110, 0x3a800000, v206
	v_cmp_gt_f32_e32 vcc, s36, v110
	v_mul_f32_e32 v112, 0x4f800000, v110
	s_nop 0
	v_cndmask_b32_e32 v110, v110, v112, vcc
	v_sqrt_f32_e32 v112, v110
	s_nop 0
	v_add_u32_e32 v132, -1, v112
	v_fma_f32 v133, -v132, v112, v110
	v_cmp_ge_f32_e64 s[6:7], 0, v133
	v_add_u32_e32 v133, 1, v112
	s_nop 0
	v_cndmask_b32_e64 v132, v112, v132, s[6:7]
	v_fma_f32 v112, -v133, v112, v110
	v_cmp_lt_f32_e64 s[6:7], 0, v112
	s_nop 1
	v_cndmask_b32_e64 v112, v132, v133, s[6:7]
	v_mul_f32_e32 v132, 0x37800000, v112
	v_cndmask_b32_e32 v112, v112, v132, vcc
	v_cmp_class_f32_e32 vcc, v110, v205
	s_nop 1
	v_cndmask_b32_e32 v110, v112, v110, vcc
	v_div_scale_f32 v112, s[6:7], v110, v110, 1.0
	v_rcp_f32_e32 v132, v112
	s_nop 0
	v_fma_f32 v133, -v112, v132, 1.0
	v_fmac_f32_e32 v132, v133, v132
	v_div_scale_f32 v133, vcc, 1.0, v110, 1.0
	v_mul_f32_e32 v134, v133, v132
	v_fma_f32 v135, -v112, v134, v133
	v_fmac_f32_e32 v134, v135, v132
	v_fma_f32 v112, -v112, v134, v133
	v_div_fmas_f32 v112, v112, v132, v134
	v_div_fixup_f32 v112, v112, v110, 1.0
	v_pk_mul_f32 v[122:123], v[112:113], v[122:123] op_sel_hi:[0,1]
	v_pk_mul_f32 v[124:125], v[112:113], v[124:125] op_sel_hi:[0,1]
	v_lshl_add_u64 v[132:133], s[26:27], 0, v[0:1]
	v_pk_fma_f32 v[80:81], v[4:5], v[124:125], v[80:81]
	v_pk_fma_f32 v[78:79], v[2:3], v[122:123], v[78:79]
	global_store_dwordx4 v[132:133], v[78:81], off nt
	v_mov_b32_e32 v110, v113
	s_nop 0
	v_mov_b32_e32 v78, v114
	v_mov_b32_e32 v79, v116
	v_mov_b32_e32 v116, v115
	v_pk_mul_f32 v[78:79], v[112:113], v[78:79] op_sel_hi:[0,1]
	v_pk_mul_f32 v[80:81], v[112:113], v[116:117] op_sel_hi:[0,1]
	v_pk_fma_f32 v[76:77], v[8:9], v[80:81], v[76:77]
	v_pk_fma_f32 v[74:75], v[6:7], v[78:79], v[74:75]
	global_store_dwordx4 v[132:133], v[74:77], off offset:1024 nt
	s_waitcnt vmcnt(25)
	v_lshlrev_b32_e32 v80, 16, v104
	v_and_b32_e32 v81, 0xffff0000, v104
	v_pk_mul_f32 v[74:75], v[112:113], v[118:119] op_sel_hi:[0,1]
	v_pk_mul_f32 v[76:77], v[112:113], v[120:121] op_sel_hi:[0,1]
	v_pk_fma_f32 v[72:73], v[12:13], v[76:77], v[72:73]
	v_pk_fma_f32 v[70:71], v[10:11], v[74:75], v[70:71]
	global_store_dwordx4 v[132:133], v[70:73], off offset:2048 nt
	v_lshlrev_b32_e32 v104, 16, v105
	v_and_b32_e32 v105, 0xffff0000, v105
	v_pk_mul_f32 v[70:71], v[110:111], v[112:113] op_sel_hi:[1,0]
	v_pk_mul_f32 v[72:73], v[108:109], v[112:113] op_sel_hi:[1,0]
	v_pk_fma_f32 v[66:67], v[14:15], v[70:71], v[66:67]
	v_pk_fma_f32 v[68:69], v[16:17], v[72:73], v[68:69]
	global_store_dwordx4 v[132:133], v[66:69], off offset:3072 nt
	s_waitcnt vmcnt(25)
	v_and_b32_e32 v79, 0xffff0000, v107
	v_and_b32_e32 v78, 0xffff0000, v106
	v_mul_f32_e32 v66, v105, v105
	v_pk_fma_f32 v[108:109], v[104:105], v[104:105], v[66:67] op_sel_hi:[1,1,0]
	v_lshlrev_b32_e32 v77, 16, v107
	v_lshlrev_b32_e32 v76, 16, v106
	v_pk_mul_f32 v[66:67], v[78:79], v[78:79]
	s_waitcnt vmcnt(21)
	v_and_b32_e32 v69, 0xffff0000, v100
	v_mul_f32_e32 v68, v81, v81
	v_pk_fma_f32 v[106:107], v[76:77], v[76:77], v[66:67]
	v_lshlrev_b32_e32 v71, 16, v100
	v_lshlrev_b32_e32 v66, 16, v101
	v_and_b32_e32 v67, 0xffff0000, v101
	v_pk_fma_f32 v[100:101], v[80:81], v[80:81], v[68:69] op_sel_hi:[1,1,0]
	v_lshlrev_b32_e32 v72, 16, v102
	v_and_b32_e32 v73, 0xffff0000, v102
	v_lshlrev_b32_e32 v74, 16, v103
	v_and_b32_e32 v75, 0xffff0000, v103
	v_mov_b32_e32 v70, v100
	v_mov_b32_e32 v102, v108
	v_mov_b32_e32 v103, v71
	v_pk_add_f32 v[100:101], v[100:101], v[108:109]
	v_pk_mul_f32 v[102:103], v[70:71], v[102:103]
	v_mul_f32_e32 v110, v69, v69
	v_mov_b32_e32 v101, v103
	v_pk_add_f32 v[102:103], v[106:107], v[106:107] op_sel:[0,1] op_sel_hi:[1,0]
	v_mul_f32_e32 v68, v73, v73
	v_mov_b32_e32 v103, v110
	v_pk_add_f32 v[100:101], v[100:101], v[102:103]
	v_pk_fma_f32 v[102:103], v[72:73], v[72:73], v[68:69] op_sel_hi:[1,1,0]
	v_mul_f32_e32 v68, v75, v75
	v_mul_f32_e32 v111, v66, v66
	v_mul_f32_e32 v112, v67, v67
	v_pk_fma_f32 v[106:107], v[74:75], v[74:75], v[68:69] op_sel_hi:[1,1,0]
	v_mov_b32_e32 v103, v111
	v_mov_b32_e32 v107, v112
	v_pk_add_f32 v[102:103], v[102:103], v[106:107]
	s_nop 0
	v_pk_add_f32 v[100:101], v[100:101], v[102:103]
	s_nop 0
	v_add_f32_e32 v68, v100, v101
	s_nop 1
	v_mov_b32_dpp v70, v68 quad_perm:[1,0,3,2] row_mask:0xf bank_mask:0xf
	s_waitcnt lgkmcnt(0)
	v_add_f32_e32 v68, v68, v70
	s_nop 1
	v_mov_b32_dpp v70, v68 quad_perm:[2,3,0,1] row_mask:0xf bank_mask:0xf
	s_waitcnt lgkmcnt(0)
	v_add_f32_e32 v68, v68, v70
	s_nop 1
	v_mov_b32_dpp v70, v68 row_half_mirror row_mask:0xf bank_mask:0xf
	s_waitcnt lgkmcnt(0)
	v_add_f32_e32 v68, v68, v70
	s_nop 1
	v_mov_b32_dpp v70, v68 row_ror:8 row_mask:0xf bank_mask:0xf
	s_waitcnt lgkmcnt(0)
	v_add_f32_e32 v68, v68, v70
	v_mov_b32_e32 v70, v68
	s_nop 1
	v_permlane16_swap_b32_e32 v70, v68
	s_waitcnt lgkmcnt(0)
	v_add_f32_e32 v68, v68, v70
	v_mov_b32_e32 v70, v68
	s_nop 1
	v_permlane32_swap_b32_e32 v70, v68
	s_waitcnt lgkmcnt(0)
; __device__ __forceinline__ float bf_lo(unsigned w) { return __uint_as_float(w << 16); }
; __device__ __forceinline__ float bf_hi(unsigned w) { return __uint_as_float(w & 0xffff0000u); }
; __device__ __forceinline__ float shx(float v, int o, int lane) { return __int_as_float(__builtin_amdgcn_ds_bpermute((lane ^ o) << 2, __float_as_int(v))); }
; __device__ __forceinline__ float wave_sum(float v, int lane) {
; #pragma unroll
;     for (int o = 1; o < 64; o <<= 1) v += shx(v, o, lane);
;     return v;
; __device__ __forceinline__ void phase_f(const float* x, float* out, const bf16_t* ob, int ldo, const float* g_post, int gw, int ngw) {
;     ...
;         for (int q = 0; q < 4; ++q) { float s = 0.f; f32x4 f[4];
; #pragma unroll
;             for (int j = 0; j < 4; ++j) { f[j] = (f32x4){bf_lo(v[q][j].x), bf_hi(v[q][j].x), bf_lo(v[q][j].y), bf_hi(v[q][j].y)}; s += (f[j].x * f[j].x + f[j].y * f[j].y) + (f[j].z * f[j].z + f[j].w * f[j].w); }
;             const float r = 1.0f / sqrtf(wave_sum(s, lane) * (1.0f / DM) + EPS);
;             f32x4* orow = (f32x4*)(out + (size_t)(m0 + q) * DM) + lane;
; #pragma unroll
;             for (int j = 0; j < 4; ++j) __builtin_nontemporal_store(xv[q][j] + f[j] * r * gp[j], orow + 64 * j); }
	v_add_f32_e32 v68, v68, v70
	v_fmamk_f32 v68, v68, 0x3a800000, v206
	v_cmp_gt_f32_e32 vcc, s36, v68
	v_mul_f32_e32 v70, 0x4f800000, v68
	s_nop 0
	v_cndmask_b32_e32 v68, v68, v70, vcc
	v_sqrt_f32_e32 v70, v68
	s_nop 0
	v_add_u32_e32 v100, -1, v70
	v_fma_f32 v101, -v100, v70, v68
	v_cmp_ge_f32_e64 s[6:7], 0, v101
	v_add_u32_e32 v101, 1, v70
	s_nop 0
	v_cndmask_b32_e64 v100, v70, v100, s[6:7]
	v_fma_f32 v70, -v101, v70, v68
	v_cmp_lt_f32_e64 s[6:7], 0, v70
	s_nop 1
	v_cndmask_b32_e64 v70, v100, v101, s[6:7]
	v_mul_f32_e32 v100, 0x37800000, v70
	v_cndmask_b32_e32 v70, v70, v100, vcc
	v_cmp_class_f32_e32 vcc, v68, v205
	s_nop 1
	v_cndmask_b32_e32 v68, v70, v68, vcc
	v_div_scale_f32 v70, s[6:7], v68, v68, 1.0
	v_rcp_f32_e32 v100, v70
	s_nop 0
	v_fma_f32 v101, -v70, v100, 1.0
	v_fmac_f32_e32 v100, v101, v100
	v_div_scale_f32 v101, vcc, 1.0, v68, 1.0
	v_mul_f32_e32 v102, v101, v100
	v_fma_f32 v103, -v70, v102, v101
	v_fmac_f32_e32 v102, v103, v100
	v_fma_f32 v70, -v70, v102, v101
	v_div_fmas_f32 v70, v70, v100, v102
	v_div_fixup_f32 v70, v70, v68, 1.0
	v_pk_mul_f32 v[80:81], v[70:71], v[80:81] op_sel_hi:[0,1]
	v_pk_mul_f32 v[102:103], v[70:71], v[104:105] op_sel_hi:[0,1]
	v_lshl_add_u64 v[100:101], s[66:67], 0, v[0:1]
	v_pk_fma_f32 v[64:65], v[4:5], v[102:103], v[64:65]
	v_pk_fma_f32 v[62:63], v[2:3], v[80:81], v[62:63]
	global_store_dwordx4 v[100:101], v[62:65], off nt
	v_mov_b32_e32 v68, v71
	s_nop 0
	v_mov_b32_e32 v62, v76
	v_mov_b32_e32 v63, v78
	v_mov_b32_e32 v78, v77
	v_pk_mul_f32 v[62:63], v[70:71], v[62:63] op_sel_hi:[0,1]
	v_pk_mul_f32 v[64:65], v[70:71], v[78:79] op_sel_hi:[0,1]
	v_pk_fma_f32 v[60:61], v[8:9], v[64:65], v[60:61]
	v_pk_fma_f32 v[58:59], v[6:7], v[62:63], v[58:59]
	v_lshl_add_u64 v[62:63], s[68:69], 0, v[0:1]
	global_store_dwordx4 v[62:63], v[58:61], off nt
	s_waitcnt vmcnt(21)
	v_and_b32_e32 v65, 0xffff0000, v98
	v_lshlrev_b32_e32 v64, 16, v98
	v_pk_mul_f32 v[58:59], v[70:71], v[72:73] op_sel_hi:[0,1]
	v_pk_mul_f32 v[60:61], v[70:71], v[74:75] op_sel_hi:[0,1]
	v_pk_fma_f32 v[56:57], v[12:13], v[60:61], v[56:57]
	v_pk_fma_f32 v[54:55], v[10:11], v[58:59], v[54:55]
	v_lshl_add_u64 v[58:59], s[70:71], 0, v[0:1]
	global_store_dwordx4 v[58:59], v[54:57], off nt
	s_waitcnt vmcnt(20)
	v_and_b32_e32 v59, 0xffff0000, v97
	v_and_b32_e32 v58, 0xffff0000, v96
	v_pk_mul_f32 v[54:55], v[68:69], v[70:71] op_sel_hi:[1,0]
	v_pk_mul_f32 v[56:57], v[66:67], v[70:71] op_sel_hi:[1,0]
	v_pk_fma_f32 v[50:51], v[14:15], v[54:55], v[50:51]
	v_pk_fma_f32 v[52:53], v[16:17], v[56:57], v[52:53]
	v_lshl_add_u64 v[54:55], s[64:65], 0, v[0:1]
	v_and_b32_e32 v67, 0xffff0000, v99
	global_store_dwordx4 v[54:55], v[50:53], off nt
	v_lshlrev_b32_e32 v66, 16, v99
	v_lshlrev_b32_e32 v57, 16, v97
	v_mul_f32_e32 v50, v67, v67
	s_waitcnt vmcnt(17)
	v_and_b32_e32 v53, 0xffff0000, v92
	v_mul_f32_e32 v52, v65, v65
	v_pk_fma_f32 v[68:69], v[66:67], v[66:67], v[50:51] op_sel_hi:[1,1,0]
	v_lshlrev_b32_e32 v56, 16, v96
	v_pk_mul_f32 v[50:51], v[58:59], v[58:59]
	v_lshlrev_b32_e32 v55, 16, v92
	v_pk_fma_f32 v[72:73], v[64:65], v[64:65], v[52:53] op_sel_hi:[1,1,0]
	v_pk_fma_f32 v[70:71], v[56:57], v[56:57], v[50:51]
	v_mov_b32_e32 v54, v72
	v_mov_b32_e32 v74, v68
	v_mov_b32_e32 v75, v55
	v_and_b32_e32 v61, 0xffff0000, v94
	v_mul_f32_e32 v76, v53, v53
	v_pk_add_f32 v[68:69], v[72:73], v[68:69]
	v_pk_mul_f32 v[72:73], v[54:55], v[74:75]
	v_pk_add_f32 v[70:71], v[70:71], v[70:71] op_sel:[0,1] op_sel_hi:[1,0]
	v_lshlrev_b32_e32 v60, 16, v94
	v_and_b32_e32 v63, 0xffff0000, v95
	v_mov_b32_e32 v69, v73
	v_mov_b32_e32 v71, v76
	v_mul_f32_e32 v52, v61, v61
	v_lshlrev_b32_e32 v62, 16, v95
	v_lshlrev_b32_e32 v50, 16, v93
	v_and_b32_e32 v51, 0xffff0000, v93
	v_pk_add_f32 v[68:69], v[68:69], v[70:71]
	v_pk_fma_f32 v[70:71], v[60:61], v[60:61], v[52:53] op_sel_hi:[1,1,0]
	v_mul_f32_e32 v52, v63, v63
	v_mul_f32_e32 v77, v50, v50
	v_mul_f32_e32 v78, v51, v51
	v_pk_fma_f32 v[72:73], v[62:63], v[62:63], v[52:53] op_sel_hi:[1,1,0]
	v_mov_b32_e32 v71, v77
	v_mov_b32_e32 v73, v78
	v_pk_add_f32 v[70:71], v[70:71], v[72:73]
	s_nop 0
	v_pk_add_f32 v[68:69], v[68:69], v[70:71]
	s_nop 0
	v_add_f32_e32 v52, v68, v69
	s_nop 1
	v_mov_b32_dpp v54, v52 quad_perm:[1,0,3,2] row_mask:0xf bank_mask:0xf
	s_waitcnt lgkmcnt(0)
	v_add_f32_e32 v52, v52, v54
	s_nop 1
	v_mov_b32_dpp v54, v52 quad_perm:[2,3,0,1] row_mask:0xf bank_mask:0xf
	s_waitcnt lgkmcnt(0)
	v_add_f32_e32 v52, v52, v54
	s_nop 1
	v_mov_b32_dpp v54, v52 row_half_mirror row_mask:0xf bank_mask:0xf
	s_waitcnt lgkmcnt(0)
	v_add_f32_e32 v52, v52, v54
	s_nop 1
	v_mov_b32_dpp v54, v52 row_ror:8 row_mask:0xf bank_mask:0xf
	s_waitcnt lgkmcnt(0)
	v_add_f32_e32 v52, v52, v54
	v_mov_b32_e32 v54, v52
	s_nop 1
	v_permlane16_swap_b32_e32 v54, v52
	s_waitcnt lgkmcnt(0)
	v_add_f32_e32 v52, v52, v54
	v_mov_b32_e32 v54, v52
	s_nop 1
	v_permlane32_swap_b32_e32 v54, v52
	s_waitcnt lgkmcnt(0)
; __device__ __forceinline__ float bf_lo(unsigned w) { return __uint_as_float(w << 16); }
; __device__ __forceinline__ float bf_hi(unsigned w) { return __uint_as_float(w & 0xffff0000u); }
; __device__ __forceinline__ float shx(float v, int o, int lane) { return __int_as_float(__builtin_amdgcn_ds_bpermute((lane ^ o) << 2, __float_as_int(v))); }
; __device__ __forceinline__ float wave_sum(float v, int lane) {
; #pragma unroll
;     for (int o = 1; o < 64; o <<= 1) v += shx(v, o, lane);
;     return v;
; __device__ __forceinline__ void phase_f(const float* x, float* out, const bf16_t* ob, int ldo, const float* g_post, int gw, int ngw) {
;     ...
;         for (int q = 0; q < 4; ++q) { float s = 0.f; f32x4 f[4];
; #pragma unroll
;             for (int j = 0; j < 4; ++j) { f[j] = (f32x4){bf_lo(v[q][j].x), bf_hi(v[q][j].x), bf_lo(v[q][j].y), bf_hi(v[q][j].y)}; s += (f[j].x * f[j].x + f[j].y * f[j].y) + (f[j].z * f[j].z + f[j].w * f[j].w); }
;             const float r = 1.0f / sqrtf(wave_sum(s, lane) * (1.0f / DM) + EPS);
;             f32x4* orow = (f32x4*)(out + (size_t)(m0 + q) * DM) + lane;
; #pragma unroll
;             for (int j = 0; j < 4; ++j) __builtin_nontemporal_store(xv[q][j] + f[j] * r * gp[j], orow + 64 * j); }
	v_add_f32_e32 v52, v52, v54
	v_fmamk_f32 v52, v52, 0x3a800000, v206
	v_cmp_gt_f32_e32 vcc, s36, v52
	v_mul_f32_e32 v54, 0x4f800000, v52
	s_nop 0
	v_cndmask_b32_e32 v52, v52, v54, vcc
	v_sqrt_f32_e32 v54, v52
	s_nop 0
	v_add_u32_e32 v68, -1, v54
	v_fma_f32 v69, -v68, v54, v52
	v_cmp_ge_f32_e64 s[6:7], 0, v69
	v_add_u32_e32 v69, 1, v54
	s_nop 0
	v_cndmask_b32_e64 v68, v54, v68, s[6:7]
	v_fma_f32 v54, -v69, v54, v52
	v_cmp_lt_f32_e64 s[6:7], 0, v54
	s_nop 1
	v_cndmask_b32_e64 v54, v68, v69, s[6:7]
	v_mul_f32_e32 v68, 0x37800000, v54
	v_cndmask_b32_e32 v54, v54, v68, vcc
	v_cmp_class_f32_e32 vcc, v52, v205
	s_nop 1
	v_cndmask_b32_e32 v52, v54, v52, vcc
	v_div_scale_f32 v54, s[6:7], v52, v52, 1.0
	v_rcp_f32_e32 v68, v54
	s_nop 0
	v_fma_f32 v69, -v54, v68, 1.0
	v_fmac_f32_e32 v68, v69, v68
	v_div_scale_f32 v69, vcc, 1.0, v52, 1.0
	v_mul_f32_e32 v70, v69, v68
	v_fma_f32 v71, -v54, v70, v69
	v_fmac_f32_e32 v70, v71, v68
	v_fma_f32 v54, -v54, v70, v69
	v_div_fmas_f32 v54, v54, v68, v70
	v_div_fixup_f32 v54, v54, v52, 1.0
	v_pk_mul_f32 v[64:65], v[54:55], v[64:65] op_sel_hi:[0,1]
	v_pk_mul_f32 v[66:67], v[54:55], v[66:67] op_sel_hi:[0,1]
	v_lshl_add_u64 v[68:69], s[24:25], 0, v[0:1]
	v_pk_fma_f32 v[48:49], v[4:5], v[66:67], v[48:49]
	v_pk_fma_f32 v[46:47], v[2:3], v[64:65], v[46:47]
	global_store_dwordx4 v[68:69], v[46:49], off nt
	v_mov_b32_e32 v52, v55
	s_nop 0
	v_mov_b32_e32 v46, v56
	v_mov_b32_e32 v47, v58
	v_mov_b32_e32 v58, v57
	v_pk_mul_f32 v[46:47], v[54:55], v[46:47] op_sel_hi:[0,1]
	v_pk_mul_f32 v[48:49], v[54:55], v[58:59] op_sel_hi:[0,1]
	v_pk_fma_f32 v[44:45], v[8:9], v[48:49], v[44:45]
	v_pk_fma_f32 v[42:43], v[6:7], v[46:47], v[42:43]
	global_store_dwordx4 v[68:69], v[42:45], off offset:1024 nt
	s_waitcnt vmcnt(17)
	v_and_b32_e32 v49, 0xffff0000, v84
	v_lshlrev_b32_e32 v48, 16, v84
	v_pk_mul_f32 v[42:43], v[54:55], v[60:61] op_sel_hi:[0,1]
	v_pk_mul_f32 v[44:45], v[54:55], v[62:63] op_sel_hi:[0,1]
	v_pk_fma_f32 v[40:41], v[12:13], v[44:45], v[40:41]
	v_pk_fma_f32 v[38:39], v[10:11], v[42:43], v[38:39]
	global_store_dwordx4 v[68:69], v[38:41], off offset:2048 nt
	s_waitcnt vmcnt(16)
	v_and_b32_e32 v43, 0xffff0000, v87
	v_and_b32_e32 v42, 0xffff0000, v86
	v_pk_mul_f32 v[38:39], v[52:53], v[54:55] op_sel_hi:[1,0]
	v_pk_mul_f32 v[40:41], v[50:51], v[54:55] op_sel_hi:[1,0]
	v_pk_fma_f32 v[34:35], v[14:15], v[38:39], v[34:35]
	v_pk_fma_f32 v[36:37], v[16:17], v[40:41], v[36:37]
	v_and_b32_e32 v51, 0xffff0000, v85
	global_store_dwordx4 v[68:69], v[34:37], off offset:3072 nt
	v_lshlrev_b32_e32 v50, 16, v85
	v_lshlrev_b32_e32 v41, 16, v87
	v_mul_f32_e32 v34, v51, v51
	s_waitcnt vmcnt(13)
	v_and_b32_e32 v37, 0xffff0000, v90
	v_mul_f32_e32 v36, v49, v49
	v_pk_fma_f32 v[52:53], v[50:51], v[50:51], v[34:35] op_sel_hi:[1,1,0]
	v_lshlrev_b32_e32 v40, 16, v86
	v_pk_mul_f32 v[34:35], v[42:43], v[42:43]
	v_lshlrev_b32_e32 v39, 16, v90
	v_pk_fma_f32 v[56:57], v[48:49], v[48:49], v[36:37] op_sel_hi:[1,1,0]
	v_pk_fma_f32 v[54:55], v[40:41], v[40:41], v[34:35]
	v_mov_b32_e32 v38, v56
	v_mov_b32_e32 v58, v52
	v_mov_b32_e32 v59, v39
	v_and_b32_e32 v45, 0xffff0000, v88
	v_mul_f32_e32 v60, v37, v37
	v_pk_add_f32 v[52:53], v[56:57], v[52:53]
	v_pk_mul_f32 v[56:57], v[38:39], v[58:59]
	v_pk_add_f32 v[54:55], v[54:55], v[54:55] op_sel:[0,1] op_sel_hi:[1,0]
	v_lshlrev_b32_e32 v44, 16, v88
	v_and_b32_e32 v47, 0xffff0000, v89
	v_mov_b32_e32 v53, v57
	v_mov_b32_e32 v55, v60
	v_mul_f32_e32 v36, v45, v45
	v_lshlrev_b32_e32 v46, 16, v89
	v_lshlrev_b32_e32 v34, 16, v91
	v_and_b32_e32 v35, 0xffff0000, v91
	v_pk_add_f32 v[52:53], v[52:53], v[54:55]
	v_pk_fma_f32 v[54:55], v[44:45], v[44:45], v[36:37] op_sel_hi:[1,1,0]
	v_mul_f32_e32 v36, v47, v47
	v_mul_f32_e32 v61, v34, v34
	v_mul_f32_e32 v62, v35, v35
	v_pk_fma_f32 v[56:57], v[46:47], v[46:47], v[36:37] op_sel_hi:[1,1,0]
	v_mov_b32_e32 v55, v61
	v_mov_b32_e32 v57, v62
	v_pk_add_f32 v[54:55], v[54:55], v[56:57]
	s_nop 0
	v_pk_add_f32 v[52:53], v[52:53], v[54:55]
	s_nop 0
	v_add_f32_e32 v36, v52, v53
	s_nop 1
	v_mov_b32_dpp v38, v36 quad_perm:[1,0,3,2] row_mask:0xf bank_mask:0xf
	s_waitcnt lgkmcnt(0)
; __device__ __forceinline__ float bf_lo(unsigned w) { return __uint_as_float(w << 16); }
; __device__ __forceinline__ float bf_hi(unsigned w) { return __uint_as_float(w & 0xffff0000u); }
; __device__ __forceinline__ float shx(float v, int o, int lane) { return __int_as_float(__builtin_amdgcn_ds_bpermute((lane ^ o) << 2, __float_as_int(v))); }
; __device__ __forceinline__ float wave_sum(float v, int lane) {
; #pragma unroll
;     for (int o = 1; o < 64; o <<= 1) v += shx(v, o, lane);
;     return v;
; __device__ __forceinline__ void phase_f(const float* x, float* out, const bf16_t* ob, int ldo, const float* g_post, int gw, int ngw) {
;     ...
;         for (int q = 0; q < 4; ++q) { float s = 0.f; f32x4 f[4];
; #pragma unroll
;             for (int j = 0; j < 4; ++j) { f[j] = (f32x4){bf_lo(v[q][j].x), bf_hi(v[q][j].x), bf_lo(v[q][j].y), bf_hi(v[q][j].y)}; s += (f[j].x * f[j].x + f[j].y * f[j].y) + (f[j].z * f[j].z + f[j].w * f[j].w); }
;             const float r = 1.0f / sqrtf(wave_sum(s, lane) * (1.0f / DM) + EPS);
;             f32x4* orow = (f32x4*)(out + (size_t)(m0 + q) * DM) + lane;
; #pragma unroll
;             for (int j = 0; j < 4; ++j) __builtin_nontemporal_store(xv[q][j] + f[j] * r * gp[j], orow + 64 * j); }
	v_add_f32_e32 v36, v36, v38
	s_nop 1
	v_mov_b32_dpp v38, v36 quad_perm:[2,3,0,1] row_mask:0xf bank_mask:0xf
	s_waitcnt lgkmcnt(0)
	v_add_f32_e32 v36, v36, v38
	s_nop 1
	v_mov_b32_dpp v38, v36 row_half_mirror row_mask:0xf bank_mask:0xf
	s_waitcnt lgkmcnt(0)
	v_add_f32_e32 v36, v36, v38
	s_nop 1
	v_mov_b32_dpp v38, v36 row_ror:8 row_mask:0xf bank_mask:0xf
	s_waitcnt lgkmcnt(0)
	v_add_f32_e32 v36, v36, v38
	v_mov_b32_e32 v38, v36
	s_nop 1
	v_permlane16_swap_b32_e32 v38, v36
	s_waitcnt lgkmcnt(0)
	v_add_f32_e32 v36, v36, v38
	v_mov_b32_e32 v38, v36
	s_nop 1
	v_permlane32_swap_b32_e32 v38, v36
	s_waitcnt lgkmcnt(0)
	v_add_f32_e32 v36, v36, v38
	v_fmamk_f32 v36, v36, 0x3a800000, v206
	v_cmp_gt_f32_e32 vcc, s36, v36
	v_mul_f32_e32 v38, 0x4f800000, v36
	s_nop 0
	v_cndmask_b32_e32 v36, v36, v38, vcc
	v_sqrt_f32_e32 v38, v36
	s_nop 0
	v_add_u32_e32 v52, -1, v38
	v_fma_f32 v53, -v52, v38, v36
	v_cmp_ge_f32_e64 s[6:7], 0, v53
	v_add_u32_e32 v53, 1, v38
	s_nop 0
	v_cndmask_b32_e64 v52, v38, v52, s[6:7]
	v_fma_f32 v38, -v53, v38, v36
	v_cmp_lt_f32_e64 s[6:7], 0, v38
	s_nop 1
	v_cndmask_b32_e64 v38, v52, v53, s[6:7]
	v_mul_f32_e32 v52, 0x37800000, v38
	v_cndmask_b32_e32 v38, v38, v52, vcc
	v_cmp_class_f32_e32 vcc, v36, v205
	s_nop 1
	v_cndmask_b32_e32 v36, v38, v36, vcc
	v_div_scale_f32 v38, s[6:7], v36, v36, 1.0
	v_rcp_f32_e32 v52, v38
	s_nop 0
	v_fma_f32 v53, -v38, v52, 1.0
	v_fmac_f32_e32 v52, v53, v52
	v_div_scale_f32 v53, vcc, 1.0, v36, 1.0
	v_mul_f32_e32 v54, v53, v52
	v_fma_f32 v55, -v38, v54, v53
	v_fmac_f32_e32 v54, v55, v52
	v_fma_f32 v38, -v38, v54, v53
	v_div_fmas_f32 v38, v38, v52, v54
	v_lshl_add_u64 v[52:53], s[20:21], 0, v[0:1]
	s_add_u32 s20, s20, s52
	s_addc_u32 s21, s21, s53
	s_add_u32 s24, s24, s52
	s_addc_u32 s25, s25, s53
	s_add_u32 s26, s26, s52
	v_div_fixup_f32 v38, v38, v36, 1.0
	s_addc_u32 s27, s27, s53
	v_pk_mul_f32 v[48:49], v[38:39], v[48:49] op_sel_hi:[0,1]
	v_pk_mul_f32 v[50:51], v[38:39], v[50:51] op_sel_hi:[0,1]
	s_add_u32 s66, s66, s52
	v_pk_fma_f32 v[20:21], v[4:5], v[50:51], v[20:21]
	v_pk_fma_f32 v[18:19], v[2:3], v[48:49], v[18:19]
	s_addc_u32 s67, s67, s53
	global_store_dwordx4 v[52:53], v[18:21], off offset:-3072 nt
	s_add_u32 s68, s68, s52
	s_addc_u32 s69, s69, s53
	v_mov_b32_e32 v18, v40
	v_mov_b32_e32 v19, v42
	v_mov_b32_e32 v42, v41
	v_pk_mul_f32 v[18:19], v[38:39], v[18:19] op_sel_hi:[0,1]
	v_pk_mul_f32 v[20:21], v[38:39], v[42:43] op_sel_hi:[0,1]
	v_pk_fma_f32 v[20:21], v[8:9], v[20:21], v[24:25]
	v_pk_fma_f32 v[18:19], v[6:7], v[18:19], v[22:23]
	s_add_u32 s70, s70, s52
	global_store_dwordx4 v[52:53], v[18:21], off offset:-2048 nt
	s_addc_u32 s71, s71, s53
	v_mov_b32_e32 v36, v39
	v_pk_mul_f32 v[18:19], v[38:39], v[44:45] op_sel_hi:[0,1]
	v_pk_mul_f32 v[20:21], v[38:39], v[46:47] op_sel_hi:[0,1]
	v_pk_fma_f32 v[20:21], v[12:13], v[20:21], v[28:29]
	v_pk_fma_f32 v[18:19], v[10:11], v[18:19], v[26:27]
	s_add_u32 s64, s64, s52
	global_store_dwordx4 v[52:53], v[18:21], off offset:-1024 nt
	s_addc_u32 s65, s65, s53
	s_cmp_lt_i32 s11, 0x8000
	v_pk_mul_f32 v[18:19], v[36:37], v[38:39] op_sel_hi:[1,0]
	v_pk_mul_f32 v[20:21], v[34:35], v[38:39] op_sel_hi:[1,0]
	s_waitcnt vmcnt(15)
	v_pk_fma_f32 v[18:19], v[14:15], v[18:19], v[30:31]
	v_pk_fma_f32 v[20:21], v[16:17], v[20:21], v[32:33]
	global_store_dwordx4 v[52:53], v[18:21], off nt
	s_cbranch_scc1 .LBB0_444

; __device__ __forceinline__ unsigned cvt_pk_bf16(float lo, float hi) { f32x2 v = {lo, hi}; bf16x2_t b = __builtin_convertvector(v, bf16x2_t); return __builtin_bit_cast(unsigned, b); }
; __device__ __forceinline__ float shx(float v, int o, int lane) { return __int_as_float(__builtin_amdgcn_ds_bpermute((lane ^ o) << 2, __float_as_int(v))); }
; __device__ __forceinline__ float wave_sum(float v, int lane) {
; #pragma unroll
;     for (int o = 1; o < 64; o <<= 1) v += shx(v, o, lane);
;     return v;
; __device__ __forceinline__ void phase_a(const float* x, bf16_t* xb, float* rs, int gw, int ngw) {
;     ...
;     for (int m0 = gw * 4; m0 < GT; m0 += ngw * 4) {
;         f32x4 v[4][4];
; #pragma unroll
;         for (int q = 0; q < 4; ++q) { const f32x4* xr = (const f32x4*)(x + (size_t)(m0 + q) * DM) + lane;
; #pragma unroll
;             for (int j = 0; j < 4; ++j) v[q][j] = __builtin_nontemporal_load(xr + 64 * j); }
; #pragma unroll
;         for (int q = 0; q < 4; ++q) { float s = 0.f;
; #pragma unroll
;             for (int j = 0; j < 4; ++j) s += (v[q][j].x * v[q][j].x + v[q][j].y * v[q][j].y) + (v[q][j].z * v[q][j].z + v[q][j].w * v[q][j].w);
;             const float r = 1.0f / sqrtf(wave_sum(s, lane) * (1.0f / DM) + EPS);
;             if (lane == 0) rs[m0 + q] = r;
;             u32x2* o8 = (u32x2*)(xb + (size_t)(m0 + q) * DM) + lane;
; #pragma unroll
;             for (int j = 0; j < 4; ++j) { u32x2 w; w.x = cvt_pk_bf16(v[q][j].x, v[q][j].y); w.y = cvt_pk_bf16(v[q][j].z, v[q][j].w); o8[64 * j] = w; } }
.LBB0_449:
	v_lshl_add_u64 v[14:15], s[20:21], 0, v[0:1]
	v_add_co_u32_e32 v2, vcc, 0xffffd000, v14
	s_movk_i32 s6, 0xf000
	s_nop 0
	v_addc_co_u32_e32 v3, vcc, -1, v15, vcc
	global_load_dwordx4 v[62:65], v[2:3], off offset:-3072 nt
	global_load_dwordx4 v[58:61], v[2:3], off offset:-2048 nt
	global_load_dwordx4 v[54:57], v[2:3], off offset:-1024 nt
	global_load_dwordx4 v[50:53], v[2:3], off nt
	v_add_co_u32_e32 v2, vcc, 0xffffe000, v14
	s_waitcnt vmcnt(3)
	v_mul_f32_e32 v74, v63, v63
	v_addc_co_u32_e32 v3, vcc, -1, v15, vcc
	global_load_dwordx4 v[46:49], v[2:3], off offset:-3072 nt
	global_load_dwordx4 v[42:45], v[2:3], off offset:-2048 nt
	global_load_dwordx4 v[38:41], v[2:3], off offset:-1024 nt
	global_load_dwordx4 v[34:37], v[2:3], off nt
	v_add_co_u32_e32 v2, vcc, s6, v14
	v_mul_f32_e32 v75, v65, v65
	s_nop 0
	v_addc_co_u32_e32 v3, vcc, -1, v15, vcc
	global_load_dwordx4 v[26:29], v[2:3], off offset:-3072 nt
	global_load_dwordx4 v[22:25], v[2:3], off offset:-2048 nt
	s_waitcnt lgkmcnt(0)
	global_load_dwordx4 v[18:21], v[2:3], off offset:-1024 nt
	global_load_dwordx4 v[30:33], v[14:15], off offset:-4096 nt
	global_load_dwordx4 v[10:13], v[14:15], off offset:-3072 nt
	global_load_dwordx4 v[6:9], v[14:15], off offset:-2048 nt
	s_nop 0
	global_load_dwordx4 v[2:5], v[14:15], off offset:-1024 nt
	s_nop 0
	global_load_dwordx4 v[14:17], v[14:15], off nt
	v_fmac_f32_e32 v74, v62, v62
	v_fmac_f32_e32 v75, v64, v64
	v_add_f32_e32 v74, v74, v75
	s_waitcnt vmcnt(14)
	v_mul_f32_e32 v75, v59, v59
	v_mul_f32_e32 v76, v61, v61
	v_fmac_f32_e32 v75, v58, v58
	v_fmac_f32_e32 v76, v60, v60
	v_add_f32_e32 v75, v75, v76
	v_add_f32_e32 v74, v74, v75
	s_waitcnt vmcnt(13)
	v_mul_f32_e32 v75, v55, v55
	v_mul_f32_e32 v76, v57, v57
	v_fmac_f32_e32 v75, v54, v54
	v_fmac_f32_e32 v76, v56, v56
	v_add_f32_e32 v75, v75, v76
	v_add_f32_e32 v74, v74, v75
	s_waitcnt vmcnt(12)
	v_mul_f32_e32 v75, v51, v51
	v_mul_f32_e32 v76, v53, v53
	v_fmac_f32_e32 v75, v50, v50
	v_fmac_f32_e32 v76, v52, v52
	v_add_f32_e32 v75, v75, v76
	v_add_f32_e32 v74, v74, v75
	s_nop 1
	v_mov_b32_dpp v75, v74 quad_perm:[1,0,3,2] row_mask:0xf bank_mask:0xf
	s_waitcnt lgkmcnt(0)
	v_add_f32_e32 v74, v74, v75
	s_nop 1
	v_mov_b32_dpp v75, v74 quad_perm:[2,3,0,1] row_mask:0xf bank_mask:0xf
	s_waitcnt lgkmcnt(0)
	v_add_f32_e32 v74, v74, v75
	s_nop 1
	v_mov_b32_dpp v75, v74 row_half_mirror row_mask:0xf bank_mask:0xf
	s_waitcnt lgkmcnt(0)
	v_add_f32_e32 v74, v74, v75
	s_nop 1
	v_mov_b32_dpp v75, v74 row_ror:8 row_mask:0xf bank_mask:0xf
	s_waitcnt lgkmcnt(0)
	v_add_f32_e32 v74, v74, v75
	v_mov_b32_e32 v75, v74
	s_nop 1
	v_permlane16_swap_b32_e32 v75, v74
	s_waitcnt lgkmcnt(0)
	v_add_f32_e32 v74, v74, v75
	v_mov_b32_e32 v75, v74
	s_nop 1
	v_permlane32_swap_b32_e32 v75, v74
	s_and_saveexec_b64 s[24:25], s[4:5]
	s_cbranch_execz .LBB0_451
	s_waitcnt lgkmcnt(0)
	v_add_f32_e32 v74, v74, v75
	v_fmamk_f32 v74, v74, 0x3a800000, v206
	v_mul_f32_e32 v75, 0x4f800000, v74
	v_cmp_gt_f32_e32 vcc, s36, v74
	s_nop 1
	v_cndmask_b32_e32 v74, v74, v75, vcc
	v_sqrt_f32_e32 v75, v74
	s_nop 0
	v_add_u32_e32 v76, -1, v75
	v_fma_f32 v78, -v76, v75, v74
	v_add_u32_e32 v77, 1, v75
	v_cmp_ge_f32_e64 s[6:7], 0, v78
	s_nop 1
	v_cndmask_b32_e64 v76, v75, v76, s[6:7]
	v_fma_f32 v75, -v77, v75, v74
	v_cmp_lt_f32_e64 s[6:7], 0, v75
	s_nop 1
	v_cndmask_b32_e64 v75, v76, v77, s[6:7]
	v_mul_f32_e32 v76, 0x37800000, v75
	v_cndmask_b32_e32 v75, v75, v76, vcc
	v_cmp_class_f32_e32 vcc, v74, v205
	s_nop 1
	v_cndmask_b32_e32 v74, v75, v74, vcc
	v_div_scale_f32 v75, s[6:7], v74, v74, 1.0
	v_rcp_f32_e32 v76, v75
	s_nop 0
	v_fma_f32 v77, -v75, v76, 1.0
	v_fmac_f32_e32 v76, v77, v76
	v_div_scale_f32 v77, vcc, 1.0, v74, 1.0
	v_mul_f32_e32 v78, v77, v76
	v_fma_f32 v79, -v75, v78, v77
	v_fmac_f32_e32 v78, v79, v76
	v_fma_f32 v75, -v75, v78, v77
	v_div_fmas_f32 v75, v75, v76, v78
	v_div_fixup_f32 v74, v75, v74, 1.0
	global_store_dword v1, v74, s[12:13] offset:-12
.LBB0_451:
	s_or_b64 exec, exec, s[24:25]
	v_cvt_pk_bf16_f32 v62, v62, v63
	v_cvt_pk_bf16_f32 v63, v64, v65
	v_add_co_u32_e32 v64, vcc, 0xfffff000, v66
	v_cvt_pk_bf16_f32 v50, v50, v51
	s_nop 0
	v_addc_co_u32_e32 v65, vcc, -1, v67, vcc
	v_cvt_pk_bf16_f32 v51, v52, v53
	global_store_dwordx2 v[64:65], v[50:51], off offset:-2048
	s_waitcnt vmcnt(12)
	v_mul_f32_e32 v50, v47, v47
	v_mul_f32_e32 v51, v49, v49
	v_fmac_f32_e32 v50, v46, v46
	v_fmac_f32_e32 v51, v48, v48
	v_add_f32_e32 v50, v50, v51
	s_waitcnt vmcnt(11)
	v_mul_f32_e32 v51, v43, v43
	v_mul_f32_e32 v52, v45, v45
	v_fmac_f32_e32 v51, v42, v42
	v_fmac_f32_e32 v52, v44, v44
	v_add_f32_e32 v51, v51, v52
	v_add_f32_e32 v50, v50, v51
	s_waitcnt vmcnt(10)
	v_mul_f32_e32 v51, v39, v39
	v_mul_f32_e32 v52, v41, v41
	v_fmac_f32_e32 v51, v38, v38
	v_fmac_f32_e32 v52, v40, v40
	v_add_f32_e32 v51, v51, v52
	v_add_f32_e32 v50, v50, v51
	s_waitcnt vmcnt(9)
	v_mul_f32_e32 v51, v35, v35
	v_mul_f32_e32 v52, v37, v37
	v_fmac_f32_e32 v51, v34, v34
	v_fmac_f32_e32 v52, v36, v36
	v_add_f32_e32 v51, v51, v52
	v_add_f32_e32 v50, v50, v51
	s_nop 1
	v_mov_b32_dpp v51, v50 quad_perm:[1,0,3,2] row_mask:0xf bank_mask:0xf
	v_cvt_pk_bf16_f32 v58, v58, v59
	v_cvt_pk_bf16_f32 v59, v60, v61
	v_cvt_pk_bf16_f32 v54, v54, v55
	v_cvt_pk_bf16_f32 v55, v56, v57
	s_waitcnt lgkmcnt(0)
	v_add_f32_e32 v50, v50, v51
	s_nop 1
	v_mov_b32_dpp v51, v50 quad_perm:[2,3,0,1] row_mask:0xf bank_mask:0xf
	global_store_dwordx2 v[64:65], v[62:63], off offset:-3584
	global_store_dwordx2 v[64:65], v[58:59], off offset:-3072
	global_store_dwordx2 v[64:65], v[54:55], off offset:-2560
	s_waitcnt lgkmcnt(0)
	v_add_f32_e32 v50, v50, v51
	s_nop 1
	v_mov_b32_dpp v51, v50 row_half_mirror row_mask:0xf bank_mask:0xf
	s_waitcnt lgkmcnt(0)
	v_add_f32_e32 v50, v50, v51
	s_nop 1
	v_mov_b32_dpp v51, v50 row_ror:8 row_mask:0xf bank_mask:0xf
	s_waitcnt lgkmcnt(0)
	v_add_f32_e32 v50, v50, v51
	v_mov_b32_e32 v51, v50
	s_nop 1
	v_permlane16_swap_b32_e32 v51, v50
	s_waitcnt lgkmcnt(0)
	v_add_f32_e32 v50, v50, v51
	v_mov_b32_e32 v51, v50
	s_nop 1
	v_permlane32_swap_b32_e32 v51, v50
	s_and_saveexec_b64 s[24:25], s[4:5]
	s_cbranch_execz .LBB0_453
; __device__ __forceinline__ unsigned cvt_pk_bf16(float lo, float hi) { f32x2 v = {lo, hi}; bf16x2_t b = __builtin_convertvector(v, bf16x2_t); return __builtin_bit_cast(unsigned, b); }
; __device__ __forceinline__ float shx(float v, int o, int lane) { return __int_as_float(__builtin_amdgcn_ds_bpermute((lane ^ o) << 2, __float_as_int(v))); }
; __device__ __forceinline__ float wave_sum(float v, int lane) {
; #pragma unroll
;     for (int o = 1; o < 64; o <<= 1) v += shx(v, o, lane);
;     return v;
; __device__ __forceinline__ void phase_a(const float* x, bf16_t* xb, float* rs, int gw, int ngw) {
;     ...
;         for (int q = 0; q < 4; ++q) { float s = 0.f;
; #pragma unroll
;             for (int j = 0; j < 4; ++j) s += (v[q][j].x * v[q][j].x + v[q][j].y * v[q][j].y) + (v[q][j].z * v[q][j].z + v[q][j].w * v[q][j].w);
;             const float r = 1.0f / sqrtf(wave_sum(s, lane) * (1.0f / DM) + EPS);
;             if (lane == 0) rs[m0 + q] = r;
;             u32x2* o8 = (u32x2*)(xb + (size_t)(m0 + q) * DM) + lane;
; #pragma unroll
;             for (int j = 0; j < 4; ++j) { u32x2 w; w.x = cvt_pk_bf16(v[q][j].x, v[q][j].y); w.y = cvt_pk_bf16(v[q][j].z, v[q][j].w); o8[64 * j] = w; } }
	s_waitcnt lgkmcnt(0)
	v_add_f32_e32 v50, v50, v51
	v_fmamk_f32 v50, v50, 0x3a800000, v206
	v_mul_f32_e32 v51, 0x4f800000, v50
	v_cmp_gt_f32_e32 vcc, s36, v50
	s_nop 1
	v_cndmask_b32_e32 v50, v50, v51, vcc
	v_sqrt_f32_e32 v51, v50
	s_nop 0
	v_add_u32_e32 v52, -1, v51
	v_fma_f32 v54, -v52, v51, v50
	v_add_u32_e32 v53, 1, v51
	v_cmp_ge_f32_e64 s[6:7], 0, v54
	s_nop 1
	v_cndmask_b32_e64 v52, v51, v52, s[6:7]
	v_fma_f32 v51, -v53, v51, v50
	v_cmp_lt_f32_e64 s[6:7], 0, v51
	s_nop 1
	v_cndmask_b32_e64 v51, v52, v53, s[6:7]
	v_mul_f32_e32 v52, 0x37800000, v51
	v_cndmask_b32_e32 v51, v51, v52, vcc
	v_cmp_class_f32_e32 vcc, v50, v205
	s_nop 1
	v_cndmask_b32_e32 v50, v51, v50, vcc
	v_div_scale_f32 v51, s[6:7], v50, v50, 1.0
	v_rcp_f32_e32 v52, v51
	s_nop 0
	v_fma_f32 v53, -v51, v52, 1.0
	v_fmac_f32_e32 v52, v53, v52
	v_div_scale_f32 v53, vcc, 1.0, v50, 1.0
	v_mul_f32_e32 v54, v53, v52
	v_fma_f32 v55, -v51, v54, v53
	v_fmac_f32_e32 v54, v55, v52
	v_fma_f32 v51, -v51, v54, v53
	v_div_fmas_f32 v51, v51, v52, v54
	v_div_fixup_f32 v50, v51, v50, 1.0
	global_store_dword v1, v50, s[12:13] offset:-8
.LBB0_453:
	s_or_b64 exec, exec, s[24:25]
	v_cvt_pk_bf16_f32 v34, v34, v35
	v_cvt_pk_bf16_f32 v35, v36, v37
	global_store_dwordx2 v[66:67], v[34:35], off offset:-4096
	s_waitcnt vmcnt(12)
	v_mul_f32_e32 v34, v27, v27
	v_mul_f32_e32 v35, v29, v29
	v_fmac_f32_e32 v34, v26, v26
	v_fmac_f32_e32 v35, v28, v28
	v_add_f32_e32 v34, v34, v35
	s_waitcnt vmcnt(11)
	v_mul_f32_e32 v35, v23, v23
	v_mul_f32_e32 v36, v25, v25
	v_fmac_f32_e32 v35, v22, v22
	v_fmac_f32_e32 v36, v24, v24
	v_add_f32_e32 v35, v35, v36
	v_add_f32_e32 v34, v34, v35
	s_waitcnt vmcnt(10)
	v_mul_f32_e32 v35, v19, v19
	v_mul_f32_e32 v36, v21, v21
	v_fmac_f32_e32 v35, v18, v18
	v_fmac_f32_e32 v36, v20, v20
	v_add_f32_e32 v35, v35, v36
	v_add_f32_e32 v34, v34, v35
	s_waitcnt vmcnt(9)
	v_mul_f32_e32 v35, v31, v31
	v_mul_f32_e32 v36, v33, v33
	v_fmac_f32_e32 v35, v30, v30
	v_fmac_f32_e32 v36, v32, v32
	v_add_f32_e32 v35, v35, v36
	v_add_f32_e32 v34, v34, v35
	s_nop 1
	v_mov_b32_dpp v35, v34 quad_perm:[1,0,3,2] row_mask:0xf bank_mask:0xf
	v_cvt_pk_bf16_f32 v46, v46, v47
	v_cvt_pk_bf16_f32 v47, v48, v49
	v_add_co_u32_e32 v48, vcc, 0xfffff000, v66
	s_waitcnt lgkmcnt(0)
	v_add_f32_e32 v34, v34, v35
	s_nop 1
	v_mov_b32_dpp v35, v34 quad_perm:[2,3,0,1] row_mask:0xf bank_mask:0xf
	v_addc_co_u32_e32 v49, vcc, -1, v67, vcc
	v_cvt_pk_bf16_f32 v42, v42, v43
	v_cvt_pk_bf16_f32 v43, v44, v45
	s_waitcnt lgkmcnt(0)
	v_add_f32_e32 v34, v34, v35
	s_nop 1
	v_mov_b32_dpp v35, v34 row_half_mirror row_mask:0xf bank_mask:0xf
	v_cvt_pk_bf16_f32 v38, v38, v39
	v_cvt_pk_bf16_f32 v39, v40, v41
	global_store_dwordx2 v[48:49], v[46:47], off offset:-1536
	global_store_dwordx2 v[48:49], v[42:43], off offset:-1024
	s_waitcnt lgkmcnt(0)
	v_add_f32_e32 v34, v34, v35
	s_nop 1
	v_mov_b32_dpp v35, v34 row_ror:8 row_mask:0xf bank_mask:0xf
	global_store_dwordx2 v[48:49], v[38:39], off offset:-512
	s_waitcnt lgkmcnt(0)
	v_add_f32_e32 v34, v34, v35
	v_mov_b32_e32 v35, v34
	s_nop 1
	v_permlane16_swap_b32_e32 v35, v34
	s_waitcnt lgkmcnt(0)
	v_add_f32_e32 v34, v34, v35
	v_mov_b32_e32 v35, v34
	s_nop 1
	v_permlane32_swap_b32_e32 v35, v34
	s_and_saveexec_b64 s[24:25], s[4:5]
	s_cbranch_execz .LBB0_455
	s_waitcnt lgkmcnt(0)
	v_add_f32_e32 v34, v34, v35
	v_fmamk_f32 v34, v34, 0x3a800000, v206
	v_mul_f32_e32 v35, 0x4f800000, v34
	v_cmp_gt_f32_e32 vcc, s36, v34
	s_nop 1
	v_cndmask_b32_e32 v34, v34, v35, vcc
	v_sqrt_f32_e32 v35, v34
	s_nop 0
	v_add_u32_e32 v36, -1, v35
	v_fma_f32 v38, -v36, v35, v34
	v_add_u32_e32 v37, 1, v35
	v_cmp_ge_f32_e64 s[6:7], 0, v38
	s_nop 1
	v_cndmask_b32_e64 v36, v35, v36, s[6:7]
	v_fma_f32 v35, -v37, v35, v34
	v_cmp_lt_f32_e64 s[6:7], 0, v35
	s_nop 1
	v_cndmask_b32_e64 v35, v36, v37, s[6:7]
	v_mul_f32_e32 v36, 0x37800000, v35
	v_cndmask_b32_e32 v35, v35, v36, vcc
	v_cmp_class_f32_e32 vcc, v34, v205
	s_nop 1
	v_cndmask_b32_e32 v34, v35, v34, vcc
	v_div_scale_f32 v35, s[6:7], v34, v34, 1.0
	v_rcp_f32_e32 v36, v35
	s_nop 0
	v_fma_f32 v37, -v35, v36, 1.0
	v_fmac_f32_e32 v36, v37, v36
	v_div_scale_f32 v37, vcc, 1.0, v34, 1.0
	v_mul_f32_e32 v38, v37, v36
	v_fma_f32 v39, -v35, v38, v37
	v_fmac_f32_e32 v38, v39, v36
	v_fma_f32 v35, -v35, v38, v37
	v_div_fmas_f32 v35, v35, v36, v38
	v_div_fixup_f32 v34, v35, v34, 1.0
	global_store_dword v1, v34, s[12:13] offset:-4
; __device__ __forceinline__ unsigned cvt_pk_bf16(float lo, float hi) { f32x2 v = {lo, hi}; bf16x2_t b = __builtin_convertvector(v, bf16x2_t); return __builtin_bit_cast(unsigned, b); }
; __device__ __forceinline__ float shx(float v, int o, int lane) { return __int_as_float(__builtin_amdgcn_ds_bpermute((lane ^ o) << 2, __float_as_int(v))); }
; __device__ __forceinline__ float wave_sum(float v, int lane) {
; #pragma unroll
;     for (int o = 1; o < 64; o <<= 1) v += shx(v, o, lane);
;     return v;
; __device__ __forceinline__ void phase_a(const float* x, bf16_t* xb, float* rs, int gw, int ngw) {
;     ...
;         for (int q = 0; q < 4; ++q) { float s = 0.f;
; #pragma unroll
;             for (int j = 0; j < 4; ++j) s += (v[q][j].x * v[q][j].x + v[q][j].y * v[q][j].y) + (v[q][j].z * v[q][j].z + v[q][j].w * v[q][j].w);
;             const float r = 1.0f / sqrtf(wave_sum(s, lane) * (1.0f / DM) + EPS);
;             if (lane == 0) rs[m0 + q] = r;
;             u32x2* o8 = (u32x2*)(xb + (size_t)(m0 + q) * DM) + lane;
; #pragma unroll
;             for (int j = 0; j < 4; ++j) { u32x2 w; w.x = cvt_pk_bf16(v[q][j].x, v[q][j].y); w.y = cvt_pk_bf16(v[q][j].z, v[q][j].w); o8[64 * j] = w; } }
.LBB0_455:
	s_or_b64 exec, exec, s[24:25]
	v_cvt_pk_bf16_f32 v18, v18, v19
	v_cvt_pk_bf16_f32 v19, v20, v21
	global_store_dwordx2 v[66:67], v[18:19], off offset:-2560
	v_cvt_pk_bf16_f32 v18, v30, v31
	v_cvt_pk_bf16_f32 v19, v32, v33
	global_store_dwordx2 v[66:67], v[18:19], off offset:-2048
	s_waitcnt vmcnt(13)
	v_mul_f32_e32 v18, v11, v11
	v_mul_f32_e32 v19, v13, v13
	v_fmac_f32_e32 v18, v10, v10
	v_fmac_f32_e32 v19, v12, v12
	v_add_f32_e32 v18, v18, v19
	s_waitcnt vmcnt(12)
	v_mul_f32_e32 v19, v7, v7
	v_mul_f32_e32 v20, v9, v9
	v_fmac_f32_e32 v19, v6, v6
	v_fmac_f32_e32 v20, v8, v8
	v_add_f32_e32 v19, v19, v20
	v_add_f32_e32 v18, v18, v19
	s_waitcnt vmcnt(11)
	v_mul_f32_e32 v19, v3, v3
	v_mul_f32_e32 v20, v5, v5
	v_fmac_f32_e32 v19, v2, v2
	v_fmac_f32_e32 v20, v4, v4
	v_add_f32_e32 v19, v19, v20
	v_add_f32_e32 v18, v18, v19
	s_waitcnt vmcnt(10)
	v_mul_f32_e32 v19, v15, v15
	v_mul_f32_e32 v20, v17, v17
	v_fmac_f32_e32 v19, v14, v14
	v_fmac_f32_e32 v20, v16, v16
	v_add_f32_e32 v19, v19, v20
	v_add_f32_e32 v18, v18, v19
	s_nop 1
	v_mov_b32_dpp v19, v18 quad_perm:[1,0,3,2] row_mask:0xf bank_mask:0xf
	v_cvt_pk_bf16_f32 v26, v26, v27
	v_cvt_pk_bf16_f32 v27, v28, v29
	v_cvt_pk_bf16_f32 v22, v22, v23
	v_cvt_pk_bf16_f32 v23, v24, v25
	s_waitcnt lgkmcnt(0)
	v_add_f32_e32 v18, v18, v19
	s_nop 1
	v_mov_b32_dpp v19, v18 quad_perm:[2,3,0,1] row_mask:0xf bank_mask:0xf
	global_store_dwordx2 v[66:67], v[26:27], off offset:-3584
	global_store_dwordx2 v[66:67], v[22:23], off offset:-3072
	s_waitcnt lgkmcnt(0)
	v_add_f32_e32 v18, v18, v19
	s_nop 1
	v_mov_b32_dpp v19, v18 row_half_mirror row_mask:0xf bank_mask:0xf
	s_waitcnt lgkmcnt(0)
	v_add_f32_e32 v18, v18, v19
	s_nop 1
	v_mov_b32_dpp v19, v18 row_ror:8 row_mask:0xf bank_mask:0xf
	s_waitcnt lgkmcnt(0)
	v_add_f32_e32 v18, v18, v19
	v_mov_b32_e32 v19, v18
	s_nop 1
	v_permlane16_swap_b32_e32 v19, v18
	s_waitcnt lgkmcnt(0)
	v_add_f32_e32 v18, v18, v19
	v_mov_b32_e32 v19, v18
	s_nop 1
	v_permlane32_swap_b32_e32 v19, v18
	s_and_saveexec_b64 s[24:25], s[4:5]
	s_cbranch_execz .LBB0_448
	s_waitcnt lgkmcnt(0)
	v_add_f32_e32 v18, v18, v19
	v_fmamk_f32 v18, v18, 0x3a800000, v206
	v_mul_f32_e32 v19, 0x4f800000, v18
	v_cmp_gt_f32_e32 vcc, s36, v18
	s_nop 1
	v_cndmask_b32_e32 v18, v18, v19, vcc
	v_sqrt_f32_e32 v19, v18
	s_nop 0
	v_add_u32_e32 v20, -1, v19
	v_fma_f32 v22, -v20, v19, v18
	v_add_u32_e32 v21, 1, v19
	v_cmp_ge_f32_e64 s[6:7], 0, v22
	s_nop 1
	v_cndmask_b32_e64 v20, v19, v20, s[6:7]
	v_fma_f32 v19, -v21, v19, v18
	v_cmp_lt_f32_e64 s[6:7], 0, v19
	s_nop 1
	v_cndmask_b32_e64 v19, v20, v21, s[6:7]
	v_mul_f32_e32 v20, 0x37800000, v19
	v_cndmask_b32_e32 v19, v19, v20, vcc
	v_cmp_class_f32_e32 vcc, v18, v205
	s_nop 1
	v_cndmask_b32_e32 v18, v19, v18, vcc
	v_div_scale_f32 v19, s[6:7], v18, v18, 1.0
	v_rcp_f32_e32 v20, v19
	s_nop 0
	v_fma_f32 v21, -v19, v20, 1.0
	v_fmac_f32_e32 v20, v21, v20
	v_div_scale_f32 v21, vcc, 1.0, v18, 1.0
	v_mul_f32_e32 v22, v21, v20
	v_fma_f32 v23, -v19, v22, v21
	v_fmac_f32_e32 v22, v23, v20
	v_fma_f32 v19, -v19, v22, v21
	v_div_fmas_f32 v19, v19, v20, v22
	v_div_fixup_f32 v18, v19, v18, 1.0
	global_store_dword v1, v18, s[12:13]
	s_branch .LBB0_448
